# K-loop: the barrier that opens each 32-MFMA block moved 2 MFMAs down (wave starts its MFMAs once its own fragments are in registers), on top of coalesced epilogue stores
# speedup vs baseline: 1.0176x; 1.0041x over previous
; #define PG8_STAGE(bufoff, gbase, voff) do { _Pragma("unroll") for (int _i = 0; _i < 2; ++_i) \
;         __builtin_amdgcn_global_load_lds((const unsigned*)((const char*)(gbase) + (voff)[_i]), (PG8_LAS unsigned*)(lds + (bufoff) + ldsw + _i * 8192), 16, 0, 0); } while (0)
; #define PG8_LDA(dst, b, h) do { _Pragma("unroll") for (int m = 0; m < 4; ++m) _Pragma("unroll") for (int k = 0; k < 2; ++k) dst[m][k] = *(const PG8_LAS bf16x8*)(lds + PG8_SA(b, h) + aoff + m * 2048 + k * 1024); } while (0)
; #define PG8_LDB(dst, b, h) do { _Pragma("unroll") for (int n = 0; n < 2; ++n) _Pragma("unroll") for (int k = 0; k < 2; ++k) dst[n][k] = *(const PG8_LAS bf16x8*)(lds + PG8_SB(b, h) + boff + n * 2048 + k * 1024); } while (0)
; #define PG8_MMA(ai, bj, At, Bt) do { __builtin_amdgcn_s_setprio(1); _Pragma("unroll") for (int m = 0; m < 4; ++m) _Pragma("unroll") for (int n = 0; n < 2; ++n) _Pragma("unroll") for (int k = 0; k < 2; ++k) \
;         acc[ai][bj][m][n] = __builtin_amdgcn_mfma_f32_16x16x32_bf16(Bt[n][k], At[m][k], acc[ai][bj][m][n], 0, 0, 0); __builtin_amdgcn_s_setprio(0); } while (0)
; #define PG8_WAIT_V(n) asm volatile("s_waitcnt vmcnt(" #n ")" ::: "memory")
; #define PG8_WAIT_L(n) asm volatile("s_waitcnt lgkmcnt(" #n ")" ::: "memory")
; #define PG8_BAR __builtin_amdgcn_s_barrier()
; #define PG8_SCHED __builtin_amdgcn_sched_barrier(0)
; template <class Epi, class Sched, bool ALIGN_EPI = false, bool SP2 = false>
; __device__ __forceinline__ void gemm_phase(PG8_LAS unsigned char* lds, const Gemm g, const Sched& S, const Epi& E, const int wid_in) {
;     ...
;             PG8_LDB(B0, 0, 0); PG8_LDB(B1, 0, 1); PG8_SCHED; PG8_LDA(At, 0, 0); PG8_STAGE(PG8_SA(1, 1), a1 + hstepA, voffA);
;             PG8_WAIT_V(8); PG8_WAIT_L(0); PG8_BAR; PG8_MMA(0, 0, At, B0); PG8_MMA(0, 1, At, B1); PG8_BAR; PG8_SCHED;
;             PG8_LDA(At, 0, 1); PG8_STAGE(PG8_SB(0, 0), b2, voffB); PG8_STAGE(PG8_SB(0, 1), b2 + hstep, voffB); PG8_STAGE(PG8_SA(0, 0), a2, voffA);
;             PG8_WAIT_V(8); PG8_WAIT_L(0); PG8_BAR; PG8_MMA(1, 0, At, B0); PG8_MMA(1, 1, At, B1); PG8_BAR; PG8_SCHED;
.LBB0_119:
	s_add_u32 s2, s4, 0xfff80080
	s_addc_u32 s3, s5, -1
	s_add_i32 s47, 0, 0x10000
	s_cmp_eq_u32 s46, 28
	s_cselect_b32 s23, s17, s3
	s_cselect_b32 s22, s42, s2
	s_cselect_b32 s3, s15, s45
	s_cselect_b32 s2, s43, s44
	s_add_i32 s50, 0, 0x14000
	v_add_u32_e32 v142, s47, v202
	s_waitcnt lgkmcnt(0)
	v_add_u32_e32 v184, s50, v202
	ds_read_b128 v[130:133], v142
	ds_read_b128 v[134:137], v142 offset:1024
	ds_read_b128 v[138:141], v142 offset:2048
	ds_read_b128 v[142:145], v142 offset:3072
	ds_read_b128 v[146:149], v184
	ds_read_b128 v[150:153], v184 offset:1024
	ds_read_b128 v[180:183], v184 offset:2048
	ds_read_b128 v[184:187], v184 offset:3072
	v_lshl_add_u64 v[234:235], s[4:5], 0, v[176:177]
	s_add_i32 m0, s34, 0xc000
	ds_read_b128 v[188:191], v205
	ds_read_b128 v[206:209], v205 offset:1024
	ds_read_b128 v[210:213], v205 offset:2048
	ds_read_b128 v[214:217], v205 offset:3072
	ds_read_b128 v[218:221], v205 offset:4096
	ds_read_b128 v[222:225], v205 offset:5120
	ds_read_b128 v[226:229], v205 offset:6144
	ds_read_b128 v[230:233], v205 offset:7168
	global_load_lds_dwordx4 v[234:235], off
	v_lshl_add_u64 v[234:235], s[4:5], 0, v[178:179]
	s_add_i32 m0, s34, 0xe000
	s_nop 0
	global_load_lds_dwordx4 v[234:235], off
	s_waitcnt vmcnt(8)
	s_waitcnt lgkmcnt(0)
	s_setprio 1
	s_waitcnt lgkmcnt(0)
	v_mfma_f32_16x16x32_bf16 v[126:129], v[130:133], v[188:191], v[126:129]
	v_mfma_f32_16x16x32_bf16 v[122:125], v[138:141], v[188:191], v[122:125]
	s_barrier
	v_mfma_f32_16x16x32_bf16 v[110:113], v[130:133], v[210:213], v[110:113]
	v_mfma_f32_16x16x32_bf16 v[106:109], v[138:141], v[210:213], v[106:109]
	v_mfma_f32_16x16x32_bf16 v[94:97], v[130:133], v[218:221], v[94:97]
	v_mfma_f32_16x16x32_bf16 v[90:93], v[138:141], v[218:221], v[90:93]
	v_mfma_f32_16x16x32_bf16 v[78:81], v[130:133], v[226:229], v[78:81]
	v_mfma_f32_16x16x32_bf16 v[74:77], v[138:141], v[226:229], v[74:77]
	v_mfma_f32_16x16x32_bf16 v[126:129], v[134:137], v[206:209], v[126:129]
	v_mfma_f32_16x16x32_bf16 v[122:125], v[142:145], v[206:209], v[122:125]
	v_mfma_f32_16x16x32_bf16 v[110:113], v[134:137], v[214:217], v[110:113]
	v_mfma_f32_16x16x32_bf16 v[106:109], v[142:145], v[214:217], v[106:109]
	v_mfma_f32_16x16x32_bf16 v[94:97], v[134:137], v[222:225], v[94:97]
	v_mfma_f32_16x16x32_bf16 v[90:93], v[142:145], v[222:225], v[90:93]
	v_mfma_f32_16x16x32_bf16 v[78:81], v[134:137], v[230:233], v[78:81]
	v_mfma_f32_16x16x32_bf16 v[74:77], v[142:145], v[230:233], v[74:77]
	s_setprio 0
	s_setprio 1
	v_mfma_f32_16x16x32_bf16 v[118:121], v[146:149], v[188:191], v[118:121]
	v_mfma_f32_16x16x32_bf16 v[114:117], v[180:183], v[188:191], v[114:117]
	v_mfma_f32_16x16x32_bf16 v[102:105], v[146:149], v[210:213], v[102:105]
	v_mfma_f32_16x16x32_bf16 v[98:101], v[180:183], v[210:213], v[98:101]
	v_mfma_f32_16x16x32_bf16 v[86:89], v[146:149], v[218:221], v[86:89]
	v_mfma_f32_16x16x32_bf16 v[82:85], v[180:183], v[218:221], v[82:85]
	v_mfma_f32_16x16x32_bf16 v[70:73], v[146:149], v[226:229], v[70:73]
	v_mfma_f32_16x16x32_bf16 v[66:69], v[180:183], v[226:229], v[66:69]
	v_mfma_f32_16x16x32_bf16 v[118:121], v[150:153], v[206:209], v[118:121]
	v_mfma_f32_16x16x32_bf16 v[114:117], v[184:187], v[206:209], v[114:117]
	v_mfma_f32_16x16x32_bf16 v[102:105], v[150:153], v[214:217], v[102:105]
	v_mfma_f32_16x16x32_bf16 v[98:101], v[184:187], v[214:217], v[98:101]
	v_mfma_f32_16x16x32_bf16 v[86:89], v[150:153], v[222:225], v[86:89]
	v_mfma_f32_16x16x32_bf16 v[82:85], v[184:187], v[222:225], v[82:85]
	v_mfma_f32_16x16x32_bf16 v[70:73], v[150:153], v[230:233], v[70:73]
	v_mfma_f32_16x16x32_bf16 v[66:69], v[184:187], v[230:233], v[66:69]
	s_setprio 0
	s_barrier
	s_add_i32 s47, s47, s27
	v_lshl_add_u64 v[234:235], s[2:3], 0, v[170:171]
	s_mov_b32 m0, s47
	ds_read_b128 v[188:191], v205 offset:16384
	ds_read_b128 v[206:209], v205 offset:17408
	ds_read_b128 v[210:213], v205 offset:18432
	ds_read_b128 v[214:217], v205 offset:19456
	ds_read_b128 v[218:221], v205 offset:20480
	ds_read_b128 v[222:225], v205 offset:21504
	ds_read_b128 v[226:229], v205 offset:22528
	ds_read_b128 v[230:233], v205 offset:23552
	global_load_lds_dwordx4 v[234:235], off
	s_add_i32 m0, s47, 0x2000
	s_add_u32 s48, s2, 0x80000
	v_lshl_add_u64 v[236:237], s[2:3], 0, v[166:167]
	s_addc_u32 s49, s3, 0
	s_add_i32 s47, s50, s27
	global_load_lds_dwordx4 v[236:237], off
	v_lshl_add_u64 v[238:239], s[48:49], 0, v[170:171]
	s_mov_b32 m0, s47
	v_lshl_add_u64 v[240:241], s[22:23], 0, v[168:169]
	global_load_lds_dwordx4 v[238:239], off
	v_lshl_add_u64 v[238:239], s[48:49], 0, v[166:167]
	s_add_i32 m0, s47, 0x2000
	s_nop 0
	global_load_lds_dwordx4 v[238:239], off
	v_lshl_add_u64 v[238:239], s[22:23], 0, v[172:173]
	s_mov_b32 m0, s34
	s_nop 0
	global_load_lds_dwordx4 v[238:239], off
	s_mov_b32 m0, s35
	s_nop 0
	global_load_lds_dwordx4 v[240:241], off
	s_waitcnt vmcnt(8)
	s_waitcnt lgkmcnt(0)
	s_setprio 1
	s_waitcnt lgkmcnt(0)
	v_mfma_f32_16x16x32_bf16 v[62:65], v[130:133], v[188:191], v[62:65]
	v_mfma_f32_16x16x32_bf16 v[58:61], v[138:141], v[188:191], v[58:61]
	s_barrier
; #define PG8_STAGE(bufoff, gbase, voff) do { _Pragma("unroll") for (int _i = 0; _i < 2; ++_i) \
;         __builtin_amdgcn_global_load_lds((const unsigned*)((const char*)(gbase) + (voff)[_i]), (PG8_LAS unsigned*)(lds + (bufoff) + ldsw + _i * 8192), 16, 0, 0); } while (0)
; #define PG8_LDA(dst, b, h) do { _Pragma("unroll") for (int m = 0; m < 4; ++m) _Pragma("unroll") for (int k = 0; k < 2; ++k) dst[m][k] = *(const PG8_LAS bf16x8*)(lds + PG8_SA(b, h) + aoff + m * 2048 + k * 1024); } while (0)
; #define PG8_LDB(dst, b, h) do { _Pragma("unroll") for (int n = 0; n < 2; ++n) _Pragma("unroll") for (int k = 0; k < 2; ++k) dst[n][k] = *(const PG8_LAS bf16x8*)(lds + PG8_SB(b, h) + boff + n * 2048 + k * 1024); } while (0)
; #define PG8_MMA(ai, bj, At, Bt) do { __builtin_amdgcn_s_setprio(1); _Pragma("unroll") for (int m = 0; m < 4; ++m) _Pragma("unroll") for (int n = 0; n < 2; ++n) _Pragma("unroll") for (int k = 0; k < 2; ++k) \
;         acc[ai][bj][m][n] = __builtin_amdgcn_mfma_f32_16x16x32_bf16(Bt[n][k], At[m][k], acc[ai][bj][m][n], 0, 0, 0); __builtin_amdgcn_s_setprio(0); } while (0)
; #define PG8_WAIT_V(n) asm volatile("s_waitcnt vmcnt(" #n ")" ::: "memory")
; #define PG8_WAIT_L(n) asm volatile("s_waitcnt lgkmcnt(" #n ")" ::: "memory")
; #define PG8_BAR __builtin_amdgcn_s_barrier()
; #define PG8_SCHED __builtin_amdgcn_sched_barrier(0)
; template <class Epi, class Sched, bool ALIGN_EPI = false, bool SP2 = false>
; __device__ __forceinline__ void gemm_phase(PG8_LAS unsigned char* lds, const Gemm g, const Sched& S, const Epi& E, const int wid_in) {
;     ...
;             PG8_WAIT_V(8); PG8_WAIT_L(0); PG8_BAR; PG8_MMA(1, 0, At, B0); PG8_MMA(1, 1, At, B1); PG8_BAR; PG8_SCHED;
;             PG8_LDB(B0, 1, 0); PG8_LDB(B1, 1, 1); PG8_SCHED; PG8_LDA(At, 1, 0); PG8_STAGE(PG8_SA(0, 1), a2 + hstepA, voffA);
;             PG8_WAIT_V(8); PG8_WAIT_L(0); PG8_BAR; PG8_MMA(0, 0, At, B0); PG8_MMA(0, 1, At, B1); PG8_BAR; PG8_SCHED;
;             PG8_LDA(At, 1, 1); PG8_STAGE(PG8_SB(1, 0), b3, voffB); PG8_STAGE(PG8_SB(1, 1), b3 + hstep, voffB); PG8_STAGE(PG8_SA(1, 0), a3, voffA);
	v_mfma_f32_16x16x32_bf16 v[46:49], v[130:133], v[210:213], v[46:49]
	v_mfma_f32_16x16x32_bf16 v[42:45], v[138:141], v[210:213], v[42:45]
	v_mfma_f32_16x16x32_bf16 v[30:33], v[130:133], v[218:221], v[30:33]
	v_mfma_f32_16x16x32_bf16 v[26:29], v[138:141], v[218:221], v[26:29]
	v_mfma_f32_16x16x32_bf16 v[14:17], v[130:133], v[226:229], v[14:17]
	v_mfma_f32_16x16x32_bf16 v[10:13], v[138:141], v[226:229], v[10:13]
	v_mfma_f32_16x16x32_bf16 v[62:65], v[134:137], v[206:209], v[62:65]
	v_mfma_f32_16x16x32_bf16 v[58:61], v[142:145], v[206:209], v[58:61]
	v_mfma_f32_16x16x32_bf16 v[46:49], v[134:137], v[214:217], v[46:49]
	v_mfma_f32_16x16x32_bf16 v[42:45], v[142:145], v[214:217], v[42:45]
	v_mfma_f32_16x16x32_bf16 v[30:33], v[134:137], v[222:225], v[30:33]
	v_mfma_f32_16x16x32_bf16 v[26:29], v[142:145], v[222:225], v[26:29]
	v_mfma_f32_16x16x32_bf16 v[14:17], v[134:137], v[230:233], v[14:17]
	v_mfma_f32_16x16x32_bf16 v[10:13], v[142:145], v[230:233], v[10:13]
	s_setprio 0
	s_setprio 1
	v_mfma_f32_16x16x32_bf16 v[54:57], v[146:149], v[188:191], v[54:57]
	v_mfma_f32_16x16x32_bf16 v[50:53], v[180:183], v[188:191], v[50:53]
	v_mfma_f32_16x16x32_bf16 v[38:41], v[146:149], v[210:213], v[38:41]
	v_mfma_f32_16x16x32_bf16 v[34:37], v[180:183], v[210:213], v[34:37]
	v_mfma_f32_16x16x32_bf16 v[22:25], v[146:149], v[218:221], v[22:25]
	v_mfma_f32_16x16x32_bf16 v[18:21], v[180:183], v[218:221], v[18:21]
	v_mfma_f32_16x16x32_bf16 v[6:9], v[146:149], v[226:229], v[6:9]
	v_mfma_f32_16x16x32_bf16 v[2:5], v[180:183], v[226:229], v[2:5]
	v_mfma_f32_16x16x32_bf16 v[54:57], v[150:153], v[206:209], v[54:57]
	v_mfma_f32_16x16x32_bf16 v[50:53], v[184:187], v[206:209], v[50:53]
	v_mfma_f32_16x16x32_bf16 v[38:41], v[150:153], v[214:217], v[38:41]
	v_mfma_f32_16x16x32_bf16 v[34:37], v[184:187], v[214:217], v[34:37]
	v_mfma_f32_16x16x32_bf16 v[22:25], v[150:153], v[222:225], v[22:25]
	v_mfma_f32_16x16x32_bf16 v[18:21], v[184:187], v[222:225], v[18:21]
	v_mfma_f32_16x16x32_bf16 v[6:9], v[150:153], v[230:233], v[6:9]
	v_mfma_f32_16x16x32_bf16 v[2:5], v[184:187], v[230:233], v[2:5]
	s_setprio 0
	s_barrier
	s_add_i32 s47, 0, 0x18000
	s_add_i32 s48, 0, 0x1c000
	v_add_u32_e32 v142, s47, v202
	v_add_u32_e32 v184, s48, v202
	ds_read_b128 v[130:133], v142
	ds_read_b128 v[134:137], v142 offset:1024
	ds_read_b128 v[138:141], v142 offset:2048
	ds_read_b128 v[142:145], v142 offset:3072
	ds_read_b128 v[146:149], v184
	ds_read_b128 v[150:153], v184 offset:1024
	ds_read_b128 v[180:183], v184 offset:2048
	ds_read_b128 v[184:187], v184 offset:3072
	s_add_u32 s22, s22, 0x80000
	s_addc_u32 s23, s23, 0
	s_mov_b32 m0, s36
	v_lshl_add_u64 v[242:243], s[22:23], 0, v[172:173]
	ds_read_b128 v[188:191], v205 offset:32768
	ds_read_b128 v[206:209], v205 offset:33792
	ds_read_b128 v[210:213], v205 offset:34816
	ds_read_b128 v[214:217], v205 offset:35840
	ds_read_b128 v[218:221], v205 offset:36864
	ds_read_b128 v[222:225], v205 offset:37888
	ds_read_b128 v[226:229], v205 offset:38912
	ds_read_b128 v[230:233], v205 offset:39936
	global_load_lds_dwordx4 v[242:243], off
	v_lshl_add_u64 v[242:243], s[22:23], 0, v[168:169]
	s_mov_b32 m0, s37
	s_nop 0
	global_load_lds_dwordx4 v[242:243], off
	s_waitcnt vmcnt(8)
	s_waitcnt lgkmcnt(0)
	s_setprio 1
	s_waitcnt lgkmcnt(0)
	v_mfma_f32_16x16x32_bf16 v[126:129], v[130:133], v[188:191], v[126:129]
	v_mfma_f32_16x16x32_bf16 v[122:125], v[138:141], v[188:191], v[122:125]
	s_barrier
	v_mfma_f32_16x16x32_bf16 v[110:113], v[130:133], v[210:213], v[110:113]
	v_mfma_f32_16x16x32_bf16 v[106:109], v[138:141], v[210:213], v[106:109]
	v_mfma_f32_16x16x32_bf16 v[94:97], v[130:133], v[218:221], v[94:97]
	v_mfma_f32_16x16x32_bf16 v[90:93], v[138:141], v[218:221], v[90:93]
	v_mfma_f32_16x16x32_bf16 v[78:81], v[130:133], v[226:229], v[78:81]
	v_mfma_f32_16x16x32_bf16 v[74:77], v[138:141], v[226:229], v[74:77]
	v_mfma_f32_16x16x32_bf16 v[126:129], v[134:137], v[206:209], v[126:129]
	v_mfma_f32_16x16x32_bf16 v[122:125], v[142:145], v[206:209], v[122:125]
	v_mfma_f32_16x16x32_bf16 v[110:113], v[134:137], v[214:217], v[110:113]
	v_mfma_f32_16x16x32_bf16 v[106:109], v[142:145], v[214:217], v[106:109]
	v_mfma_f32_16x16x32_bf16 v[94:97], v[134:137], v[222:225], v[94:97]
	v_mfma_f32_16x16x32_bf16 v[90:93], v[142:145], v[222:225], v[90:93]
	v_mfma_f32_16x16x32_bf16 v[78:81], v[134:137], v[230:233], v[78:81]
	v_mfma_f32_16x16x32_bf16 v[74:77], v[142:145], v[230:233], v[74:77]
	s_setprio 0
	s_setprio 1
	v_mfma_f32_16x16x32_bf16 v[118:121], v[146:149], v[188:191], v[118:121]
	v_mfma_f32_16x16x32_bf16 v[114:117], v[180:183], v[188:191], v[114:117]
	v_mfma_f32_16x16x32_bf16 v[102:105], v[146:149], v[210:213], v[102:105]
	v_mfma_f32_16x16x32_bf16 v[98:101], v[180:183], v[210:213], v[98:101]
	v_mfma_f32_16x16x32_bf16 v[86:89], v[146:149], v[218:221], v[86:89]
	v_mfma_f32_16x16x32_bf16 v[82:85], v[180:183], v[218:221], v[82:85]
	v_mfma_f32_16x16x32_bf16 v[70:73], v[146:149], v[226:229], v[70:73]
	v_mfma_f32_16x16x32_bf16 v[66:69], v[180:183], v[226:229], v[66:69]
	v_mfma_f32_16x16x32_bf16 v[118:121], v[150:153], v[206:209], v[118:121]
	v_mfma_f32_16x16x32_bf16 v[114:117], v[184:187], v[206:209], v[114:117]
	v_mfma_f32_16x16x32_bf16 v[102:105], v[150:153], v[214:217], v[102:105]
	v_mfma_f32_16x16x32_bf16 v[98:101], v[184:187], v[214:217], v[98:101]
	v_mfma_f32_16x16x32_bf16 v[86:89], v[150:153], v[222:225], v[86:89]
	v_mfma_f32_16x16x32_bf16 v[82:85], v[184:187], v[222:225], v[82:85]
	v_mfma_f32_16x16x32_bf16 v[70:73], v[150:153], v[230:233], v[70:73]
	v_mfma_f32_16x16x32_bf16 v[66:69], v[184:187], v[230:233], v[66:69]
	s_setprio 0
	s_barrier
; #define PG8_STAGE(bufoff, gbase, voff) do { _Pragma("unroll") for (int _i = 0; _i < 2; ++_i) \
;         __builtin_amdgcn_global_load_lds((const unsigned*)((const char*)(gbase) + (voff)[_i]), (PG8_LAS unsigned*)(lds + (bufoff) + ldsw + _i * 8192), 16, 0, 0); } while (0)
; #define PG8_LDA(dst, b, h) do { _Pragma("unroll") for (int m = 0; m < 4; ++m) _Pragma("unroll") for (int k = 0; k < 2; ++k) dst[m][k] = *(const PG8_LAS bf16x8*)(lds + PG8_SA(b, h) + aoff + m * 2048 + k * 1024); } while (0)
; #define PG8_MMA(ai, bj, At, Bt) do { __builtin_amdgcn_s_setprio(1); _Pragma("unroll") for (int m = 0; m < 4; ++m) _Pragma("unroll") for (int n = 0; n < 2; ++n) _Pragma("unroll") for (int k = 0; k < 2; ++k) \
;         acc[ai][bj][m][n] = __builtin_amdgcn_mfma_f32_16x16x32_bf16(Bt[n][k], At[m][k], acc[ai][bj][m][n], 0, 0, 0); __builtin_amdgcn_s_setprio(0); } while (0)
; #define PG8_WAIT_V(n) asm volatile("s_waitcnt vmcnt(" #n ")" ::: "memory")
; #define PG8_WAIT_L(n) asm volatile("s_waitcnt lgkmcnt(" #n ")" ::: "memory")
; #define PG8_BAR __builtin_amdgcn_s_barrier()
; #define PG8_SCHED __builtin_amdgcn_sched_barrier(0)
; template <class Epi, class Sched, bool ALIGN_EPI = false, bool SP2 = false>
; __device__ __forceinline__ void gemm_phase(PG8_LAS unsigned char* lds, const Gemm g, const Sched& S, const Epi& E, const int wid_in) {
;     ...
;             PG8_LDA(At, 1, 1); PG8_STAGE(PG8_SB(1, 0), b3, voffB); PG8_STAGE(PG8_SB(1, 1), b3 + hstep, voffB); PG8_STAGE(PG8_SA(1, 0), a3, voffA);
;             PG8_WAIT_V(8); PG8_WAIT_L(0); PG8_BAR; PG8_MMA(1, 0, At, B0); PG8_MMA(1, 1, At, B1); PG8_BAR; PG8_SCHED;
	s_add_i32 s22, s47, s27
	v_lshl_add_u64 v[234:235], v[234:235], 0, s[98:99]
	s_mov_b32 m0, s22
	ds_read_b128 v[188:191], v205 offset:49152
	ds_read_b128 v[206:209], v205 offset:50176
	ds_read_b128 v[210:213], v205 offset:51200
	ds_read_b128 v[214:217], v205 offset:52224
	ds_read_b128 v[218:221], v205 offset:53248
	ds_read_b128 v[222:225], v205 offset:54272
	ds_read_b128 v[226:229], v205 offset:55296
	ds_read_b128 v[230:233], v205 offset:56320
	global_load_lds_dwordx4 v[234:235], off
	s_add_i32 m0, s22, 0x2000
	s_add_u32 s2, s2, 0x80080
	v_lshl_add_u64 v[234:235], v[236:237], 0, s[98:99]
	s_addc_u32 s3, s3, 0
	s_add_i32 s22, s48, s27
	global_load_lds_dwordx4 v[234:235], off
	v_lshl_add_u64 v[234:235], s[2:3], 0, v[170:171]
	s_mov_b32 m0, s22
	s_nop 0
	global_load_lds_dwordx4 v[234:235], off
	v_lshl_add_u64 v[234:235], s[2:3], 0, v[166:167]
	s_add_i32 m0, s22, 0x2000
	s_nop 0
	global_load_lds_dwordx4 v[234:235], off
	v_lshl_add_u64 v[234:235], v[238:239], 0, s[98:99]
	s_mov_b32 m0, s38
	s_nop 0
	global_load_lds_dwordx4 v[234:235], off
	v_lshl_add_u64 v[234:235], v[240:241], 0, s[98:99]
	s_mov_b32 m0, s39
	s_nop 0
	global_load_lds_dwordx4 v[234:235], off
	s_waitcnt vmcnt(8)
	s_waitcnt lgkmcnt(0)
	s_setprio 1
	s_waitcnt lgkmcnt(0)
	v_mfma_f32_16x16x32_bf16 v[62:65], v[130:133], v[188:191], v[62:65]
	v_mfma_f32_16x16x32_bf16 v[58:61], v[138:141], v[188:191], v[58:61]
	s_barrier
	v_mfma_f32_16x16x32_bf16 v[46:49], v[130:133], v[210:213], v[46:49]
	v_mfma_f32_16x16x32_bf16 v[42:45], v[138:141], v[210:213], v[42:45]
	v_mfma_f32_16x16x32_bf16 v[30:33], v[130:133], v[218:221], v[30:33]
	v_mfma_f32_16x16x32_bf16 v[26:29], v[138:141], v[218:221], v[26:29]
	v_mfma_f32_16x16x32_bf16 v[14:17], v[130:133], v[226:229], v[14:17]
	v_mfma_f32_16x16x32_bf16 v[10:13], v[138:141], v[226:229], v[10:13]
	v_mfma_f32_16x16x32_bf16 v[62:65], v[134:137], v[206:209], v[62:65]
	v_mfma_f32_16x16x32_bf16 v[58:61], v[142:145], v[206:209], v[58:61]
	v_mfma_f32_16x16x32_bf16 v[46:49], v[134:137], v[214:217], v[46:49]
	v_mfma_f32_16x16x32_bf16 v[42:45], v[142:145], v[214:217], v[42:45]
	v_mfma_f32_16x16x32_bf16 v[30:33], v[134:137], v[222:225], v[30:33]
	v_mfma_f32_16x16x32_bf16 v[26:29], v[142:145], v[222:225], v[26:29]
	v_mfma_f32_16x16x32_bf16 v[14:17], v[134:137], v[230:233], v[14:17]
	v_mfma_f32_16x16x32_bf16 v[10:13], v[142:145], v[230:233], v[10:13]
	s_setprio 0
	s_setprio 1
	v_mfma_f32_16x16x32_bf16 v[54:57], v[146:149], v[188:191], v[54:57]
	v_mfma_f32_16x16x32_bf16 v[50:53], v[180:183], v[188:191], v[50:53]
	v_mfma_f32_16x16x32_bf16 v[38:41], v[146:149], v[210:213], v[38:41]
	v_mfma_f32_16x16x32_bf16 v[34:37], v[180:183], v[210:213], v[34:37]
	v_mfma_f32_16x16x32_bf16 v[22:25], v[146:149], v[218:221], v[22:25]
	v_mfma_f32_16x16x32_bf16 v[18:21], v[180:183], v[218:221], v[18:21]
	v_mfma_f32_16x16x32_bf16 v[6:9], v[146:149], v[226:229], v[6:9]
	v_mfma_f32_16x16x32_bf16 v[2:5], v[180:183], v[226:229], v[2:5]
	v_mfma_f32_16x16x32_bf16 v[54:57], v[150:153], v[206:209], v[54:57]
	v_mfma_f32_16x16x32_bf16 v[50:53], v[184:187], v[206:209], v[50:53]
	v_mfma_f32_16x16x32_bf16 v[38:41], v[150:153], v[214:217], v[38:41]
	v_mfma_f32_16x16x32_bf16 v[34:37], v[184:187], v[214:217], v[34:37]
	v_mfma_f32_16x16x32_bf16 v[22:25], v[150:153], v[222:225], v[22:25]
	v_mfma_f32_16x16x32_bf16 v[18:21], v[184:187], v[222:225], v[18:21]
	v_mfma_f32_16x16x32_bf16 v[6:9], v[150:153], v[230:233], v[6:9]
	v_mfma_f32_16x16x32_bf16 v[2:5], v[184:187], v[230:233], v[2:5]
	s_setprio 0
	s_barrier
	s_add_i32 s46, s46, 2
	s_add_u32 s4, s4, 0x100
	s_addc_u32 s5, s5, 0
	s_add_u32 s44, s44, 0x100
	s_addc_u32 s45, s45, 0
	s_cmp_gt_u32 s46, 29
	s_cbranch_scc0 .LBB0_119
	s_and_b64 vcc, exec, s[12:13]
	s_cbranch_vccz .LBB0_122
	s_barrier

; #define PG8_STAGE(bufoff, gbase, voff) do { _Pragma("unroll") for (int _i = 0; _i < 2; ++_i) \
;         __builtin_amdgcn_global_load_lds((const unsigned*)((const char*)(gbase) + (voff)[_i]), (PG8_LAS unsigned*)(lds + (bufoff) + ldsw + _i * 8192), 16, 0, 0); } while (0)
; #define PG8_LDA(dst, b, h) do { _Pragma("unroll") for (int m = 0; m < 4; ++m) _Pragma("unroll") for (int k = 0; k < 2; ++k) dst[m][k] = *(const PG8_LAS bf16x8*)(lds + PG8_SA(b, h) + aoff + m * 2048 + k * 1024); } while (0)
; #define PG8_LDB(dst, b, h) do { _Pragma("unroll") for (int n = 0; n < 2; ++n) _Pragma("unroll") for (int k = 0; k < 2; ++k) dst[n][k] = *(const PG8_LAS bf16x8*)(lds + PG8_SB(b, h) + boff + n * 2048 + k * 1024); } while (0)
; #define PG8_MMA(ai, bj, At, Bt) do { __builtin_amdgcn_s_setprio(1); _Pragma("unroll") for (int m = 0; m < 4; ++m) _Pragma("unroll") for (int n = 0; n < 2; ++n) _Pragma("unroll") for (int k = 0; k < 2; ++k) \
;         acc[ai][bj][m][n] = __builtin_amdgcn_mfma_f32_16x16x32_bf16(Bt[n][k], At[m][k], acc[ai][bj][m][n], 0, 0, 0); __builtin_amdgcn_s_setprio(0); } while (0)
; #define PG8_WAIT_V(n) asm volatile("s_waitcnt vmcnt(" #n ")" ::: "memory")
; #define PG8_WAIT_L(n) asm volatile("s_waitcnt lgkmcnt(" #n ")" ::: "memory")
; #define PG8_BAR __builtin_amdgcn_s_barrier()
; #define PG8_SCHED __builtin_amdgcn_sched_barrier(0)
; template <class Epi, class Sched, bool ALIGN_EPI = false, bool SP2 = false>
; __device__ __forceinline__ void gemm_phase(PG8_LAS unsigned char* lds, const Gemm g, const Sched& S, const Epi& E, const int wid_in) {
;     ...
;             PG8_LDB(B0, 0, 0); PG8_LDB(B1, 0, 1); PG8_SCHED; PG8_LDA(At, 0, 0); PG8_STAGE(PG8_SA(1, 1), a1 + hstepA, voffA);
;             PG8_WAIT_V(8); PG8_WAIT_L(0); PG8_BAR; PG8_MMA(0, 0, At, B0); PG8_MMA(0, 1, At, B1); PG8_BAR; PG8_SCHED;
;             PG8_LDA(At, 0, 1); PG8_STAGE(PG8_SB(0, 0), b2, voffB); PG8_STAGE(PG8_SB(0, 1), b2 + hstep, voffB); PG8_STAGE(PG8_SA(0, 0), a2, voffA);
;             PG8_WAIT_V(8); PG8_WAIT_L(0); PG8_BAR; PG8_MMA(1, 0, At, B0); PG8_MMA(1, 1, At, B1); PG8_BAR; PG8_SCHED;
.LBB0_375:
	s_add_u32 s0, s26, 0x100
	s_addc_u32 s1, s27, 0
	s_add_i32 s51, 0, 0x10000
	s_cmp_eq_u32 s50, 28
	s_cselect_b32 s11, s23, s1
	s_cselect_b32 s10, s22, s0
	v_add_u32_e32 v145, s51, v147
	s_cselect_b32 s3, s21, s29
	s_cselect_b32 s2, s49, s28
	s_add_i32 s52, 0, 0x14000
	ds_read_b128 v[166:169], v145
	ds_read_b128 v[174:177], v145 offset:1024
	ds_read_b128 v[178:181], v145 offset:2048
	ds_read_b128 v[182:185], v145 offset:3072
	v_add_u32_e32 v145, s52, v147
	ds_read_b128 v[186:189], v145
	ds_read_b128 v[202:205], v145 offset:1024
	ds_read_b128 v[206:209], v145 offset:2048
	ds_read_b128 v[210:213], v145 offset:3072
	v_lshl_add_u64 v[152:153], s[26:27], 0, v[140:141]
	s_add_i32 m0, s38, 0xc000
	ds_read_b128 v[214:217], v150
	ds_read_b128 v[218:221], v150 offset:1024
	ds_read_b128 v[222:225], v150 offset:2048
	ds_read_b128 v[226:229], v150 offset:3072
	ds_read_b128 v[230:233], v150 offset:4096
	ds_read_b128 v[234:237], v150 offset:5120
	ds_read_b128 v[238:241], v150 offset:6144
	ds_read_b128 v[242:245], v150 offset:7168
	global_load_lds_dwordx4 v[152:153], off
	v_lshl_add_u64 v[152:153], s[26:27], 0, v[142:143]
	s_add_i32 m0, s38, 0xe000
	s_nop 0
	global_load_lds_dwordx4 v[152:153], off
	s_waitcnt vmcnt(8)
	s_waitcnt lgkmcnt(0)
	s_setprio 1
	s_waitcnt lgkmcnt(0)
	v_mfma_f32_16x16x32_bf16 v[118:121], v[166:169], v[214:217], v[118:121]
	v_mfma_f32_16x16x32_bf16 v[114:117], v[178:181], v[214:217], v[114:117]
	s_barrier
	v_mfma_f32_16x16x32_bf16 v[98:101], v[166:169], v[222:225], v[98:101]
	v_mfma_f32_16x16x32_bf16 v[106:109], v[178:181], v[222:225], v[106:109]
	v_mfma_f32_16x16x32_bf16 v[82:85], v[166:169], v[230:233], v[82:85]
	v_mfma_f32_16x16x32_bf16 v[90:93], v[178:181], v[230:233], v[90:93]
	v_mfma_f32_16x16x32_bf16 v[74:77], v[166:169], v[238:241], v[74:77]
	v_mfma_f32_16x16x32_bf16 v[66:69], v[178:181], v[238:241], v[66:69]
	v_mfma_f32_16x16x32_bf16 v[118:121], v[174:177], v[218:221], v[118:121]
	v_mfma_f32_16x16x32_bf16 v[114:117], v[182:185], v[218:221], v[114:117]
	v_mfma_f32_16x16x32_bf16 v[98:101], v[174:177], v[226:229], v[98:101]
	v_mfma_f32_16x16x32_bf16 v[106:109], v[182:185], v[226:229], v[106:109]
	v_mfma_f32_16x16x32_bf16 v[82:85], v[174:177], v[234:237], v[82:85]
	v_mfma_f32_16x16x32_bf16 v[90:93], v[182:185], v[234:237], v[90:93]
	v_mfma_f32_16x16x32_bf16 v[74:77], v[174:177], v[242:245], v[74:77]
	v_mfma_f32_16x16x32_bf16 v[66:69], v[182:185], v[242:245], v[66:69]
	s_setprio 0
	s_setprio 1
	v_mfma_f32_16x16x32_bf16 v[122:125], v[186:189], v[214:217], v[122:125]
	v_mfma_f32_16x16x32_bf16 v[126:129], v[206:209], v[214:217], v[126:129]
	v_mfma_f32_16x16x32_bf16 v[102:105], v[186:189], v[222:225], v[102:105]
	v_mfma_f32_16x16x32_bf16 v[110:113], v[206:209], v[222:225], v[110:113]
	v_mfma_f32_16x16x32_bf16 v[86:89], v[186:189], v[230:233], v[86:89]
	v_mfma_f32_16x16x32_bf16 v[94:97], v[206:209], v[230:233], v[94:97]
	v_mfma_f32_16x16x32_bf16 v[70:73], v[186:189], v[238:241], v[70:73]
	v_mfma_f32_16x16x32_bf16 v[78:81], v[206:209], v[238:241], v[78:81]
	v_mfma_f32_16x16x32_bf16 v[122:125], v[202:205], v[218:221], v[122:125]
	v_mfma_f32_16x16x32_bf16 v[126:129], v[210:213], v[218:221], v[126:129]
	v_mfma_f32_16x16x32_bf16 v[102:105], v[202:205], v[226:229], v[102:105]
	v_mfma_f32_16x16x32_bf16 v[110:113], v[210:213], v[226:229], v[110:113]
	v_mfma_f32_16x16x32_bf16 v[86:89], v[202:205], v[234:237], v[86:89]
	v_mfma_f32_16x16x32_bf16 v[94:97], v[210:213], v[234:237], v[94:97]
	v_mfma_f32_16x16x32_bf16 v[70:73], v[202:205], v[242:245], v[70:73]
	v_mfma_f32_16x16x32_bf16 v[78:81], v[210:213], v[242:245], v[78:81]
	s_setprio 0
	s_barrier
	s_add_i32 s26, s51, s37
	v_lshl_add_u64 v[152:153], s[2:3], 0, v[134:135]
	s_mov_b32 m0, s26
	ds_read_b128 v[214:217], v150 offset:16384
	ds_read_b128 v[218:221], v150 offset:17408
	ds_read_b128 v[222:225], v150 offset:18432
	ds_read_b128 v[226:229], v150 offset:19456
	ds_read_b128 v[230:233], v150 offset:20480
	ds_read_b128 v[234:237], v150 offset:21504
	ds_read_b128 v[238:241], v150 offset:22528
	ds_read_b128 v[242:245], v150 offset:23552
	global_load_lds_dwordx4 v[152:153], off
	s_add_i32 m0, s26, 0x2000
	s_add_u32 s26, s2, 0x80000
	v_lshl_add_u64 v[170:171], s[2:3], 0, v[130:131]
	s_addc_u32 s27, s3, 0
	s_add_i32 s51, s52, s37
	global_load_lds_dwordx4 v[170:171], off
	v_lshl_add_u64 v[190:191], s[26:27], 0, v[134:135]
	s_mov_b32 m0, s51
	v_lshl_add_u64 v[246:247], s[10:11], 0, v[132:133]
	global_load_lds_dwordx4 v[190:191], off
	v_lshl_add_u64 v[190:191], s[26:27], 0, v[130:131]
	s_add_i32 m0, s51, 0x2000
	s_nop 0
	global_load_lds_dwordx4 v[190:191], off
	v_lshl_add_u64 v[190:191], s[10:11], 0, v[136:137]
	s_mov_b32 m0, s38
	s_nop 0
	global_load_lds_dwordx4 v[190:191], off
	s_mov_b32 m0, s39
	s_nop 0
	global_load_lds_dwordx4 v[246:247], off
	s_waitcnt vmcnt(8)
	s_waitcnt lgkmcnt(0)
	s_setprio 1
	s_waitcnt lgkmcnt(0)
	v_mfma_f32_16x16x32_bf16 v[34:37], v[166:169], v[214:217], v[34:37]
	v_mfma_f32_16x16x32_bf16 v[46:49], v[178:181], v[214:217], v[46:49]
	s_barrier
; #define PG8_STAGE(bufoff, gbase, voff) do { _Pragma("unroll") for (int _i = 0; _i < 2; ++_i) \
;         __builtin_amdgcn_global_load_lds((const unsigned*)((const char*)(gbase) + (voff)[_i]), (PG8_LAS unsigned*)(lds + (bufoff) + ldsw + _i * 8192), 16, 0, 0); } while (0)
; #define PG8_LDA(dst, b, h) do { _Pragma("unroll") for (int m = 0; m < 4; ++m) _Pragma("unroll") for (int k = 0; k < 2; ++k) dst[m][k] = *(const PG8_LAS bf16x8*)(lds + PG8_SA(b, h) + aoff + m * 2048 + k * 1024); } while (0)
; #define PG8_LDB(dst, b, h) do { _Pragma("unroll") for (int n = 0; n < 2; ++n) _Pragma("unroll") for (int k = 0; k < 2; ++k) dst[n][k] = *(const PG8_LAS bf16x8*)(lds + PG8_SB(b, h) + boff + n * 2048 + k * 1024); } while (0)
; #define PG8_MMA(ai, bj, At, Bt) do { __builtin_amdgcn_s_setprio(1); _Pragma("unroll") for (int m = 0; m < 4; ++m) _Pragma("unroll") for (int n = 0; n < 2; ++n) _Pragma("unroll") for (int k = 0; k < 2; ++k) \
;         acc[ai][bj][m][n] = __builtin_amdgcn_mfma_f32_16x16x32_bf16(Bt[n][k], At[m][k], acc[ai][bj][m][n], 0, 0, 0); __builtin_amdgcn_s_setprio(0); } while (0)
; #define PG8_WAIT_V(n) asm volatile("s_waitcnt vmcnt(" #n ")" ::: "memory")
; #define PG8_WAIT_L(n) asm volatile("s_waitcnt lgkmcnt(" #n ")" ::: "memory")
; #define PG8_BAR __builtin_amdgcn_s_barrier()
; #define PG8_SCHED __builtin_amdgcn_sched_barrier(0)
; template <class Epi, class Sched, bool ALIGN_EPI = false, bool SP2 = false>
; __device__ __forceinline__ void gemm_phase(PG8_LAS unsigned char* lds, const Gemm g, const Sched& S, const Epi& E, const int wid_in) {
;     ...
;             PG8_WAIT_V(8); PG8_WAIT_L(0); PG8_BAR; PG8_MMA(1, 0, At, B0); PG8_MMA(1, 1, At, B1); PG8_BAR; PG8_SCHED;
;             PG8_LDB(B0, 1, 0); PG8_LDB(B1, 1, 1); PG8_SCHED; PG8_LDA(At, 1, 0); PG8_STAGE(PG8_SA(0, 1), a2 + hstepA, voffA);
;             PG8_WAIT_V(8); PG8_WAIT_L(0); PG8_BAR; PG8_MMA(0, 0, At, B0); PG8_MMA(0, 1, At, B1); PG8_BAR; PG8_SCHED;
;             PG8_LDA(At, 1, 1); PG8_STAGE(PG8_SB(1, 0), b3, voffB); PG8_STAGE(PG8_SB(1, 1), b3 + hstep, voffB); PG8_STAGE(PG8_SA(1, 0), a3, voffA);
	v_mfma_f32_16x16x32_bf16 v[10:13], v[166:169], v[222:225], v[10:13]
	v_mfma_f32_16x16x32_bf16 v[6:9], v[178:181], v[222:225], v[6:9]
	v_mfma_f32_16x16x32_bf16 v[42:45], v[166:169], v[230:233], v[42:45]
	v_mfma_f32_16x16x32_bf16 v[58:61], v[178:181], v[230:233], v[58:61]
	v_mfma_f32_16x16x32_bf16 v[22:25], v[166:169], v[238:241], v[22:25]
	v_mfma_f32_16x16x32_bf16 v[2:5], v[178:181], v[238:241], v[2:5]
	v_mfma_f32_16x16x32_bf16 v[34:37], v[174:177], v[218:221], v[34:37]
	v_mfma_f32_16x16x32_bf16 v[46:49], v[182:185], v[218:221], v[46:49]
	v_mfma_f32_16x16x32_bf16 v[10:13], v[174:177], v[226:229], v[10:13]
	v_mfma_f32_16x16x32_bf16 v[6:9], v[182:185], v[226:229], v[6:9]
	v_mfma_f32_16x16x32_bf16 v[42:45], v[174:177], v[234:237], v[42:45]
	v_mfma_f32_16x16x32_bf16 v[58:61], v[182:185], v[234:237], v[58:61]
	v_mfma_f32_16x16x32_bf16 v[22:25], v[174:177], v[242:245], v[22:25]
	v_mfma_f32_16x16x32_bf16 v[2:5], v[182:185], v[242:245], v[2:5]
	s_setprio 0
	s_setprio 1
	v_mfma_f32_16x16x32_bf16 v[38:41], v[186:189], v[214:217], v[38:41]
	v_mfma_f32_16x16x32_bf16 v[54:57], v[206:209], v[214:217], v[54:57]
	v_mfma_f32_16x16x32_bf16 v[14:17], v[186:189], v[222:225], v[14:17]
	v_mfma_f32_16x16x32_bf16 v[26:29], v[206:209], v[222:225], v[26:29]
	v_mfma_f32_16x16x32_bf16 v[50:53], v[186:189], v[230:233], v[50:53]
	v_mfma_f32_16x16x32_bf16 v[62:65], v[206:209], v[230:233], v[62:65]
	v_mfma_f32_16x16x32_bf16 v[18:21], v[186:189], v[238:241], v[18:21]
	v_mfma_f32_16x16x32_bf16 v[30:33], v[206:209], v[238:241], v[30:33]
	v_mfma_f32_16x16x32_bf16 v[38:41], v[202:205], v[218:221], v[38:41]
	v_mfma_f32_16x16x32_bf16 v[54:57], v[210:213], v[218:221], v[54:57]
	v_mfma_f32_16x16x32_bf16 v[14:17], v[202:205], v[226:229], v[14:17]
	v_mfma_f32_16x16x32_bf16 v[26:29], v[210:213], v[226:229], v[26:29]
	v_mfma_f32_16x16x32_bf16 v[50:53], v[202:205], v[234:237], v[50:53]
	v_mfma_f32_16x16x32_bf16 v[62:65], v[210:213], v[234:237], v[62:65]
	v_mfma_f32_16x16x32_bf16 v[18:21], v[202:205], v[242:245], v[18:21]
	v_mfma_f32_16x16x32_bf16 v[30:33], v[210:213], v[242:245], v[30:33]
	s_setprio 0
	s_barrier
	s_add_i32 s26, 0, 0x18000
	v_add_u32_e32 v145, s26, v147
	s_add_i32 s27, 0, 0x1c000
	ds_read_b128 v[166:169], v145
	ds_read_b128 v[174:177], v145 offset:1024
	ds_read_b128 v[178:181], v145 offset:2048
	ds_read_b128 v[182:185], v145 offset:3072
	v_add_u32_e32 v145, s27, v147
	ds_read_b128 v[186:189], v145
	ds_read_b128 v[202:205], v145 offset:1024
	ds_read_b128 v[206:209], v145 offset:2048
	ds_read_b128 v[210:213], v145 offset:3072
	s_add_u32 s10, s10, 0x140000
	s_addc_u32 s11, s11, 0
	s_mov_b32 m0, s40
	v_lshl_add_u64 v[248:249], s[10:11], 0, v[136:137]
	ds_read_b128 v[214:217], v150 offset:32768
	ds_read_b128 v[218:221], v150 offset:33792
	ds_read_b128 v[222:225], v150 offset:34816
	ds_read_b128 v[226:229], v150 offset:35840
	ds_read_b128 v[230:233], v150 offset:36864
	ds_read_b128 v[234:237], v150 offset:37888
	ds_read_b128 v[238:241], v150 offset:38912
	ds_read_b128 v[242:245], v150 offset:39936
	global_load_lds_dwordx4 v[248:249], off
	v_lshl_add_u64 v[248:249], s[10:11], 0, v[132:133]
	s_mov_b32 m0, s41
	s_nop 0
	global_load_lds_dwordx4 v[248:249], off
	s_waitcnt vmcnt(8)
	s_waitcnt lgkmcnt(0)
	s_setprio 1
	s_waitcnt lgkmcnt(0)
	v_mfma_f32_16x16x32_bf16 v[118:121], v[166:169], v[214:217], v[118:121]
	v_mfma_f32_16x16x32_bf16 v[114:117], v[178:181], v[214:217], v[114:117]
	s_barrier
	v_mfma_f32_16x16x32_bf16 v[98:101], v[166:169], v[222:225], v[98:101]
	v_mfma_f32_16x16x32_bf16 v[106:109], v[178:181], v[222:225], v[106:109]
	v_mfma_f32_16x16x32_bf16 v[82:85], v[166:169], v[230:233], v[82:85]
	v_mfma_f32_16x16x32_bf16 v[90:93], v[178:181], v[230:233], v[90:93]
	v_mfma_f32_16x16x32_bf16 v[74:77], v[166:169], v[238:241], v[74:77]
	v_mfma_f32_16x16x32_bf16 v[66:69], v[178:181], v[238:241], v[66:69]
	v_mfma_f32_16x16x32_bf16 v[118:121], v[174:177], v[218:221], v[118:121]
	v_mfma_f32_16x16x32_bf16 v[114:117], v[182:185], v[218:221], v[114:117]
	v_mfma_f32_16x16x32_bf16 v[98:101], v[174:177], v[226:229], v[98:101]
	v_mfma_f32_16x16x32_bf16 v[106:109], v[182:185], v[226:229], v[106:109]
	v_mfma_f32_16x16x32_bf16 v[82:85], v[174:177], v[234:237], v[82:85]
	v_mfma_f32_16x16x32_bf16 v[90:93], v[182:185], v[234:237], v[90:93]
	v_mfma_f32_16x16x32_bf16 v[74:77], v[174:177], v[242:245], v[74:77]
	v_mfma_f32_16x16x32_bf16 v[66:69], v[182:185], v[242:245], v[66:69]
	s_setprio 0
	s_setprio 1
	v_mfma_f32_16x16x32_bf16 v[122:125], v[186:189], v[214:217], v[122:125]
	v_mfma_f32_16x16x32_bf16 v[126:129], v[206:209], v[214:217], v[126:129]
	v_mfma_f32_16x16x32_bf16 v[102:105], v[186:189], v[222:225], v[102:105]
	v_mfma_f32_16x16x32_bf16 v[110:113], v[206:209], v[222:225], v[110:113]
	v_mfma_f32_16x16x32_bf16 v[86:89], v[186:189], v[230:233], v[86:89]
	v_mfma_f32_16x16x32_bf16 v[94:97], v[206:209], v[230:233], v[94:97]
	v_mfma_f32_16x16x32_bf16 v[70:73], v[186:189], v[238:241], v[70:73]
	v_mfma_f32_16x16x32_bf16 v[78:81], v[206:209], v[238:241], v[78:81]
	v_mfma_f32_16x16x32_bf16 v[122:125], v[202:205], v[218:221], v[122:125]
	v_mfma_f32_16x16x32_bf16 v[126:129], v[210:213], v[218:221], v[126:129]
	v_mfma_f32_16x16x32_bf16 v[102:105], v[202:205], v[226:229], v[102:105]
	v_mfma_f32_16x16x32_bf16 v[110:113], v[210:213], v[226:229], v[110:113]
	v_mfma_f32_16x16x32_bf16 v[86:89], v[202:205], v[234:237], v[86:89]
	v_mfma_f32_16x16x32_bf16 v[94:97], v[210:213], v[234:237], v[94:97]
	v_mfma_f32_16x16x32_bf16 v[70:73], v[202:205], v[242:245], v[70:73]
	v_mfma_f32_16x16x32_bf16 v[78:81], v[210:213], v[242:245], v[78:81]
	s_setprio 0
	s_barrier
; #define PG8_STAGE(bufoff, gbase, voff) do { _Pragma("unroll") for (int _i = 0; _i < 2; ++_i) \
;         __builtin_amdgcn_global_load_lds((const unsigned*)((const char*)(gbase) + (voff)[_i]), (PG8_LAS unsigned*)(lds + (bufoff) + ldsw + _i * 8192), 16, 0, 0); } while (0)
; #define PG8_LDA(dst, b, h) do { _Pragma("unroll") for (int m = 0; m < 4; ++m) _Pragma("unroll") for (int k = 0; k < 2; ++k) dst[m][k] = *(const PG8_LAS bf16x8*)(lds + PG8_SA(b, h) + aoff + m * 2048 + k * 1024); } while (0)
; #define PG8_MMA(ai, bj, At, Bt) do { __builtin_amdgcn_s_setprio(1); _Pragma("unroll") for (int m = 0; m < 4; ++m) _Pragma("unroll") for (int n = 0; n < 2; ++n) _Pragma("unroll") for (int k = 0; k < 2; ++k) \
;         acc[ai][bj][m][n] = __builtin_amdgcn_mfma_f32_16x16x32_bf16(Bt[n][k], At[m][k], acc[ai][bj][m][n], 0, 0, 0); __builtin_amdgcn_s_setprio(0); } while (0)
; #define PG8_WAIT_V(n) asm volatile("s_waitcnt vmcnt(" #n ")" ::: "memory")
; #define PG8_WAIT_L(n) asm volatile("s_waitcnt lgkmcnt(" #n ")" ::: "memory")
; #define PG8_BAR __builtin_amdgcn_s_barrier()
; #define PG8_SCHED __builtin_amdgcn_sched_barrier(0)
; template <class Epi, class Sched, bool ALIGN_EPI = false, bool SP2 = false>
; __device__ __forceinline__ void gemm_phase(PG8_LAS unsigned char* lds, const Gemm g, const Sched& S, const Epi& E, const int wid_in) {
;     ...
;             PG8_LDA(At, 1, 1); PG8_STAGE(PG8_SB(1, 0), b3, voffB); PG8_STAGE(PG8_SB(1, 1), b3 + hstep, voffB); PG8_STAGE(PG8_SA(1, 0), a3, voffA);
;             PG8_WAIT_V(8); PG8_WAIT_L(0); PG8_BAR; PG8_MMA(1, 0, At, B0); PG8_MMA(1, 1, At, B1); PG8_BAR; PG8_SCHED;
	s_add_i32 s10, s26, s37
	v_lshl_add_u64 v[152:153], v[152:153], 0, s[98:99]
	s_mov_b32 m0, s10
	ds_read_b128 v[214:217], v150 offset:49152
	ds_read_b128 v[218:221], v150 offset:50176
	ds_read_b128 v[222:225], v150 offset:51200
	ds_read_b128 v[226:229], v150 offset:52224
	ds_read_b128 v[230:233], v150 offset:53248
	ds_read_b128 v[234:237], v150 offset:54272
	ds_read_b128 v[238:241], v150 offset:55296
	ds_read_b128 v[242:245], v150 offset:56320
	global_load_lds_dwordx4 v[152:153], off
	s_add_i32 m0, s10, 0x2000
	s_add_u32 s2, s2, 0x80080
	v_lshl_add_u64 v[152:153], v[170:171], 0, s[98:99]
	s_addc_u32 s3, s3, 0
	s_add_i32 s10, s27, s37
	global_load_lds_dwordx4 v[152:153], off
	v_lshl_add_u64 v[152:153], s[2:3], 0, v[134:135]
	s_mov_b32 m0, s10
	s_nop 0
	global_load_lds_dwordx4 v[152:153], off
	v_lshl_add_u64 v[152:153], s[2:3], 0, v[130:131]
	s_add_i32 m0, s10, 0x2000
	s_nop 0
	global_load_lds_dwordx4 v[152:153], off
	v_lshl_add_u64 v[152:153], v[190:191], 0, s[98:99]
	s_mov_b32 m0, s44
	s_nop 0
	global_load_lds_dwordx4 v[152:153], off
	v_lshl_add_u64 v[152:153], v[246:247], 0, s[98:99]
	s_mov_b32 m0, s45
	s_nop 0
	global_load_lds_dwordx4 v[152:153], off
	s_waitcnt vmcnt(8)
	s_waitcnt lgkmcnt(0)
	s_setprio 1
	s_waitcnt lgkmcnt(0)
	v_mfma_f32_16x16x32_bf16 v[34:37], v[166:169], v[214:217], v[34:37]
	v_mfma_f32_16x16x32_bf16 v[46:49], v[178:181], v[214:217], v[46:49]
	s_barrier
	v_mfma_f32_16x16x32_bf16 v[10:13], v[166:169], v[222:225], v[10:13]
	v_mfma_f32_16x16x32_bf16 v[6:9], v[178:181], v[222:225], v[6:9]
	v_mfma_f32_16x16x32_bf16 v[42:45], v[166:169], v[230:233], v[42:45]
	v_mfma_f32_16x16x32_bf16 v[58:61], v[178:181], v[230:233], v[58:61]
	v_mfma_f32_16x16x32_bf16 v[22:25], v[166:169], v[238:241], v[22:25]
	v_mfma_f32_16x16x32_bf16 v[2:5], v[178:181], v[238:241], v[2:5]
	v_mfma_f32_16x16x32_bf16 v[34:37], v[174:177], v[218:221], v[34:37]
	v_mfma_f32_16x16x32_bf16 v[46:49], v[182:185], v[218:221], v[46:49]
	v_mfma_f32_16x16x32_bf16 v[10:13], v[174:177], v[226:229], v[10:13]
	v_mfma_f32_16x16x32_bf16 v[6:9], v[182:185], v[226:229], v[6:9]
	v_mfma_f32_16x16x32_bf16 v[42:45], v[174:177], v[234:237], v[42:45]
	v_mfma_f32_16x16x32_bf16 v[58:61], v[182:185], v[234:237], v[58:61]
	v_mfma_f32_16x16x32_bf16 v[22:25], v[174:177], v[242:245], v[22:25]
	v_mfma_f32_16x16x32_bf16 v[2:5], v[182:185], v[242:245], v[2:5]
	s_setprio 0
	s_setprio 1
	v_mfma_f32_16x16x32_bf16 v[38:41], v[186:189], v[214:217], v[38:41]
	v_mfma_f32_16x16x32_bf16 v[54:57], v[206:209], v[214:217], v[54:57]
	v_mfma_f32_16x16x32_bf16 v[14:17], v[186:189], v[222:225], v[14:17]
	v_mfma_f32_16x16x32_bf16 v[26:29], v[206:209], v[222:225], v[26:29]
	v_mfma_f32_16x16x32_bf16 v[50:53], v[186:189], v[230:233], v[50:53]
	v_mfma_f32_16x16x32_bf16 v[62:65], v[206:209], v[230:233], v[62:65]
	v_mfma_f32_16x16x32_bf16 v[18:21], v[186:189], v[238:241], v[18:21]
	v_mfma_f32_16x16x32_bf16 v[30:33], v[206:209], v[238:241], v[30:33]
	v_mfma_f32_16x16x32_bf16 v[38:41], v[202:205], v[218:221], v[38:41]
	v_mfma_f32_16x16x32_bf16 v[54:57], v[210:213], v[218:221], v[54:57]
	v_mfma_f32_16x16x32_bf16 v[14:17], v[202:205], v[226:229], v[14:17]
	v_mfma_f32_16x16x32_bf16 v[26:29], v[210:213], v[226:229], v[26:29]
	v_mfma_f32_16x16x32_bf16 v[50:53], v[202:205], v[234:237], v[50:53]
	v_mfma_f32_16x16x32_bf16 v[62:65], v[210:213], v[234:237], v[62:65]
	v_mfma_f32_16x16x32_bf16 v[18:21], v[202:205], v[242:245], v[18:21]
	v_mfma_f32_16x16x32_bf16 v[30:33], v[210:213], v[242:245], v[30:33]
	s_setprio 0
	s_barrier
	s_add_i32 s50, s50, 2
	s_add_u32 s28, s28, 0x100
	s_addc_u32 s29, s29, 0
	s_cmp_gt_u32 s50, 29
	s_mov_b64 s[26:27], s[0:1]
	s_cbranch_scc0 .LBB0_375
	s_and_b64 vcc, exec, s[16:17]
	s_cbranch_vccz .LBB0_378
	s_barrier

; #define PG8_STAGE(bufoff, gbase, voff) do { _Pragma("unroll") for (int _i = 0; _i < 2; ++_i) \
;         __builtin_amdgcn_global_load_lds((const unsigned*)((const char*)(gbase) + (voff)[_i]), (PG8_LAS unsigned*)(lds + (bufoff) + ldsw + _i * 8192), 16, 0, 0); } while (0)
; #define PG8_LDA(dst, b, h) do { _Pragma("unroll") for (int m = 0; m < 4; ++m) _Pragma("unroll") for (int k = 0; k < 2; ++k) dst[m][k] = *(const PG8_LAS bf16x8*)(lds + PG8_SA(b, h) + aoff + m * 2048 + k * 1024); } while (0)
; #define PG8_LDB(dst, b, h) do { _Pragma("unroll") for (int n = 0; n < 2; ++n) _Pragma("unroll") for (int k = 0; k < 2; ++k) dst[n][k] = *(const PG8_LAS bf16x8*)(lds + PG8_SB(b, h) + boff + n * 2048 + k * 1024); } while (0)
; #define PG8_MMA(ai, bj, At, Bt) do { __builtin_amdgcn_s_setprio(1); _Pragma("unroll") for (int m = 0; m < 4; ++m) _Pragma("unroll") for (int n = 0; n < 2; ++n) _Pragma("unroll") for (int k = 0; k < 2; ++k) \
;         acc[ai][bj][m][n] = __builtin_amdgcn_mfma_f32_16x16x32_bf16(Bt[n][k], At[m][k], acc[ai][bj][m][n], 0, 0, 0); __builtin_amdgcn_s_setprio(0); } while (0)
; #define PG8_WAIT_V(n) asm volatile("s_waitcnt vmcnt(" #n ")" ::: "memory")
; #define PG8_WAIT_L(n) asm volatile("s_waitcnt lgkmcnt(" #n ")" ::: "memory")
; #define PG8_BAR __builtin_amdgcn_s_barrier()
; #define PG8_SCHED __builtin_amdgcn_sched_barrier(0)
; template <class Epi, class Sched, bool ALIGN_EPI = false, bool SP2 = false>
; __device__ __forceinline__ void gemm_phase(PG8_LAS unsigned char* lds, const Gemm g, const Sched& S, const Epi& E, const int wid_in) {
;     ...
;             PG8_LDB(B0, 0, 0); PG8_LDB(B1, 0, 1); PG8_SCHED; PG8_LDA(At, 0, 0); PG8_STAGE(PG8_SA(1, 1), a1 + hstepA, voffA);
;             PG8_WAIT_V(8); PG8_WAIT_L(0); PG8_BAR; PG8_MMA(0, 0, At, B0); PG8_MMA(0, 1, At, B1); PG8_BAR; PG8_SCHED;
;             PG8_LDA(At, 0, 1); PG8_STAGE(PG8_SB(0, 0), b2, voffB); PG8_STAGE(PG8_SB(0, 1), b2 + hstep, voffB); PG8_STAGE(PG8_SA(0, 0), a2, voffA);
;             PG8_WAIT_V(8); PG8_WAIT_L(0); PG8_BAR; PG8_MMA(1, 0, At, B0); PG8_MMA(1, 1, At, B1); PG8_BAR; PG8_SCHED;
.LBB0_484:
	s_add_u32 s0, s24, 0xfff80080
	s_addc_u32 s1, s25, -1
	s_add_i32 s49, 0, 0x10000
	s_cmp_eq_u32 s48, 28
	s_cselect_b32 s3, s19, s1
	s_cselect_b32 s2, s44, s0
	v_add_u32_e32 v150, s49, v152
	s_cselect_b32 s1, s17, s47
	s_cselect_b32 s0, s45, s46
	s_add_i32 s52, 0, 0x14000
	ds_read_b128 v[142:145], v150
	ds_read_b128 v[146:149], v150 offset:1024
	ds_read_b128 v[168:171], v150 offset:2048
	ds_read_b128 v[174:177], v150 offset:3072
	v_add_u32_e32 v150, s52, v152
	ds_read_b128 v[178:181], v150
	ds_read_b128 v[182:185], v150 offset:1024
	ds_read_b128 v[186:189], v150 offset:2048
	ds_read_b128 v[202:205], v150 offset:3072
	v_lshl_add_u64 v[150:151], s[24:25], 0, v[138:139]
	s_add_i32 m0, s35, 0xc000
	ds_read_b128 v[206:209], v167
	ds_read_b128 v[210:213], v167 offset:1024
	ds_read_b128 v[214:217], v167 offset:2048
	ds_read_b128 v[218:221], v167 offset:3072
	ds_read_b128 v[222:225], v167 offset:4096
	ds_read_b128 v[226:229], v167 offset:5120
	ds_read_b128 v[230:233], v167 offset:6144
	ds_read_b128 v[234:237], v167 offset:7168
	global_load_lds_dwordx4 v[150:151], off
	v_lshl_add_u64 v[150:151], s[24:25], 0, v[140:141]
	s_add_i32 m0, s35, 0xe000
	s_nop 0
	global_load_lds_dwordx4 v[150:151], off
	s_waitcnt vmcnt(8)
	s_waitcnt lgkmcnt(0)
	s_setprio 1
	s_waitcnt lgkmcnt(0)
	v_mfma_f32_16x16x32_bf16 v[126:129], v[142:145], v[206:209], v[126:129]
	v_mfma_f32_16x16x32_bf16 v[122:125], v[168:171], v[206:209], v[122:125]
	s_barrier
	v_mfma_f32_16x16x32_bf16 v[110:113], v[142:145], v[214:217], v[110:113]
	v_mfma_f32_16x16x32_bf16 v[106:109], v[168:171], v[214:217], v[106:109]
	v_mfma_f32_16x16x32_bf16 v[94:97], v[142:145], v[222:225], v[94:97]
	v_mfma_f32_16x16x32_bf16 v[90:93], v[168:171], v[222:225], v[90:93]
	v_mfma_f32_16x16x32_bf16 v[78:81], v[142:145], v[230:233], v[78:81]
	v_mfma_f32_16x16x32_bf16 v[74:77], v[168:171], v[230:233], v[74:77]
	v_mfma_f32_16x16x32_bf16 v[126:129], v[146:149], v[210:213], v[126:129]
	v_mfma_f32_16x16x32_bf16 v[122:125], v[174:177], v[210:213], v[122:125]
	v_mfma_f32_16x16x32_bf16 v[110:113], v[146:149], v[218:221], v[110:113]
	v_mfma_f32_16x16x32_bf16 v[106:109], v[174:177], v[218:221], v[106:109]
	v_mfma_f32_16x16x32_bf16 v[94:97], v[146:149], v[226:229], v[94:97]
	v_mfma_f32_16x16x32_bf16 v[90:93], v[174:177], v[226:229], v[90:93]
	v_mfma_f32_16x16x32_bf16 v[78:81], v[146:149], v[234:237], v[78:81]
	v_mfma_f32_16x16x32_bf16 v[74:77], v[174:177], v[234:237], v[74:77]
	s_setprio 0
	s_setprio 1
	v_mfma_f32_16x16x32_bf16 v[118:121], v[178:181], v[206:209], v[118:121]
	v_mfma_f32_16x16x32_bf16 v[114:117], v[186:189], v[206:209], v[114:117]
	v_mfma_f32_16x16x32_bf16 v[102:105], v[178:181], v[214:217], v[102:105]
	v_mfma_f32_16x16x32_bf16 v[98:101], v[186:189], v[214:217], v[98:101]
	v_mfma_f32_16x16x32_bf16 v[86:89], v[178:181], v[222:225], v[86:89]
	v_mfma_f32_16x16x32_bf16 v[82:85], v[186:189], v[222:225], v[82:85]
	v_mfma_f32_16x16x32_bf16 v[70:73], v[178:181], v[230:233], v[70:73]
	v_mfma_f32_16x16x32_bf16 v[66:69], v[186:189], v[230:233], v[66:69]
	v_mfma_f32_16x16x32_bf16 v[118:121], v[182:185], v[210:213], v[118:121]
	v_mfma_f32_16x16x32_bf16 v[114:117], v[202:205], v[210:213], v[114:117]
	v_mfma_f32_16x16x32_bf16 v[102:105], v[182:185], v[218:221], v[102:105]
	v_mfma_f32_16x16x32_bf16 v[98:101], v[202:205], v[218:221], v[98:101]
	v_mfma_f32_16x16x32_bf16 v[86:89], v[182:185], v[226:229], v[86:89]
	v_mfma_f32_16x16x32_bf16 v[82:85], v[202:205], v[226:229], v[82:85]
	v_mfma_f32_16x16x32_bf16 v[70:73], v[182:185], v[234:237], v[70:73]
	v_mfma_f32_16x16x32_bf16 v[66:69], v[202:205], v[234:237], v[66:69]
	s_setprio 0
	s_barrier
	s_add_i32 s49, s49, s29
	v_lshl_add_u64 v[150:151], s[0:1], 0, v[134:135]
	s_mov_b32 m0, s49
	ds_read_b128 v[206:209], v167 offset:16384
	ds_read_b128 v[210:213], v167 offset:17408
	ds_read_b128 v[214:217], v167 offset:18432
	ds_read_b128 v[218:221], v167 offset:19456
	ds_read_b128 v[222:225], v167 offset:20480
	ds_read_b128 v[226:229], v167 offset:21504
	ds_read_b128 v[230:233], v167 offset:22528
	ds_read_b128 v[234:237], v167 offset:23552
	global_load_lds_dwordx4 v[150:151], off
	s_add_i32 m0, s49, 0x2000
	s_add_u32 s50, s0, 0x80000
	v_lshl_add_u64 v[190:191], s[0:1], 0, v[130:131]
	s_addc_u32 s51, s1, 0
	s_add_i32 s49, s52, s29
	global_load_lds_dwordx4 v[190:191], off
	v_lshl_add_u64 v[238:239], s[50:51], 0, v[134:135]
	s_mov_b32 m0, s49
	v_lshl_add_u64 v[240:241], s[2:3], 0, v[132:133]
	global_load_lds_dwordx4 v[238:239], off
	v_lshl_add_u64 v[238:239], s[50:51], 0, v[130:131]
	s_add_i32 m0, s49, 0x2000
	s_nop 0
	global_load_lds_dwordx4 v[238:239], off
	v_lshl_add_u64 v[238:239], s[2:3], 0, v[136:137]
	s_mov_b32 m0, s35
	s_nop 0
	global_load_lds_dwordx4 v[238:239], off
	s_mov_b32 m0, s36
	s_nop 0
	global_load_lds_dwordx4 v[240:241], off
	s_waitcnt vmcnt(8)
	s_waitcnt lgkmcnt(0)
	s_setprio 1
	s_waitcnt lgkmcnt(0)
	v_mfma_f32_16x16x32_bf16 v[62:65], v[142:145], v[206:209], v[62:65]
	v_mfma_f32_16x16x32_bf16 v[58:61], v[168:171], v[206:209], v[58:61]
	s_barrier
; #define PG8_STAGE(bufoff, gbase, voff) do { _Pragma("unroll") for (int _i = 0; _i < 2; ++_i) \
;         __builtin_amdgcn_global_load_lds((const unsigned*)((const char*)(gbase) + (voff)[_i]), (PG8_LAS unsigned*)(lds + (bufoff) + ldsw + _i * 8192), 16, 0, 0); } while (0)
; #define PG8_LDA(dst, b, h) do { _Pragma("unroll") for (int m = 0; m < 4; ++m) _Pragma("unroll") for (int k = 0; k < 2; ++k) dst[m][k] = *(const PG8_LAS bf16x8*)(lds + PG8_SA(b, h) + aoff + m * 2048 + k * 1024); } while (0)
; #define PG8_LDB(dst, b, h) do { _Pragma("unroll") for (int n = 0; n < 2; ++n) _Pragma("unroll") for (int k = 0; k < 2; ++k) dst[n][k] = *(const PG8_LAS bf16x8*)(lds + PG8_SB(b, h) + boff + n * 2048 + k * 1024); } while (0)
; #define PG8_MMA(ai, bj, At, Bt) do { __builtin_amdgcn_s_setprio(1); _Pragma("unroll") for (int m = 0; m < 4; ++m) _Pragma("unroll") for (int n = 0; n < 2; ++n) _Pragma("unroll") for (int k = 0; k < 2; ++k) \
;         acc[ai][bj][m][n] = __builtin_amdgcn_mfma_f32_16x16x32_bf16(Bt[n][k], At[m][k], acc[ai][bj][m][n], 0, 0, 0); __builtin_amdgcn_s_setprio(0); } while (0)
; #define PG8_WAIT_V(n) asm volatile("s_waitcnt vmcnt(" #n ")" ::: "memory")
; #define PG8_WAIT_L(n) asm volatile("s_waitcnt lgkmcnt(" #n ")" ::: "memory")
; #define PG8_BAR __builtin_amdgcn_s_barrier()
; #define PG8_SCHED __builtin_amdgcn_sched_barrier(0)
; template <class Epi, class Sched, bool ALIGN_EPI = false, bool SP2 = false>
; __device__ __forceinline__ void gemm_phase(PG8_LAS unsigned char* lds, const Gemm g, const Sched& S, const Epi& E, const int wid_in) {
;     ...
;             PG8_WAIT_V(8); PG8_WAIT_L(0); PG8_BAR; PG8_MMA(1, 0, At, B0); PG8_MMA(1, 1, At, B1); PG8_BAR; PG8_SCHED;
;             PG8_LDB(B0, 1, 0); PG8_LDB(B1, 1, 1); PG8_SCHED; PG8_LDA(At, 1, 0); PG8_STAGE(PG8_SA(0, 1), a2 + hstepA, voffA);
;             PG8_WAIT_V(8); PG8_WAIT_L(0); PG8_BAR; PG8_MMA(0, 0, At, B0); PG8_MMA(0, 1, At, B1); PG8_BAR; PG8_SCHED;
;             PG8_LDA(At, 1, 1); PG8_STAGE(PG8_SB(1, 0), b3, voffB); PG8_STAGE(PG8_SB(1, 1), b3 + hstep, voffB); PG8_STAGE(PG8_SA(1, 0), a3, voffA);
	v_mfma_f32_16x16x32_bf16 v[46:49], v[142:145], v[214:217], v[46:49]
	v_mfma_f32_16x16x32_bf16 v[42:45], v[168:171], v[214:217], v[42:45]
	v_mfma_f32_16x16x32_bf16 v[30:33], v[142:145], v[222:225], v[30:33]
	v_mfma_f32_16x16x32_bf16 v[26:29], v[168:171], v[222:225], v[26:29]
	v_mfma_f32_16x16x32_bf16 v[14:17], v[142:145], v[230:233], v[14:17]
	v_mfma_f32_16x16x32_bf16 v[10:13], v[168:171], v[230:233], v[10:13]
	v_mfma_f32_16x16x32_bf16 v[62:65], v[146:149], v[210:213], v[62:65]
	v_mfma_f32_16x16x32_bf16 v[58:61], v[174:177], v[210:213], v[58:61]
	v_mfma_f32_16x16x32_bf16 v[46:49], v[146:149], v[218:221], v[46:49]
	v_mfma_f32_16x16x32_bf16 v[42:45], v[174:177], v[218:221], v[42:45]
	v_mfma_f32_16x16x32_bf16 v[30:33], v[146:149], v[226:229], v[30:33]
	v_mfma_f32_16x16x32_bf16 v[26:29], v[174:177], v[226:229], v[26:29]
	v_mfma_f32_16x16x32_bf16 v[14:17], v[146:149], v[234:237], v[14:17]
	v_mfma_f32_16x16x32_bf16 v[10:13], v[174:177], v[234:237], v[10:13]
	s_setprio 0
	s_setprio 1
	v_mfma_f32_16x16x32_bf16 v[54:57], v[178:181], v[206:209], v[54:57]
	v_mfma_f32_16x16x32_bf16 v[50:53], v[186:189], v[206:209], v[50:53]
	v_mfma_f32_16x16x32_bf16 v[38:41], v[178:181], v[214:217], v[38:41]
	v_mfma_f32_16x16x32_bf16 v[34:37], v[186:189], v[214:217], v[34:37]
	v_mfma_f32_16x16x32_bf16 v[22:25], v[178:181], v[222:225], v[22:25]
	v_mfma_f32_16x16x32_bf16 v[18:21], v[186:189], v[222:225], v[18:21]
	v_mfma_f32_16x16x32_bf16 v[6:9], v[178:181], v[230:233], v[6:9]
	v_mfma_f32_16x16x32_bf16 v[2:5], v[186:189], v[230:233], v[2:5]
	v_mfma_f32_16x16x32_bf16 v[54:57], v[182:185], v[210:213], v[54:57]
	v_mfma_f32_16x16x32_bf16 v[50:53], v[202:205], v[210:213], v[50:53]
	v_mfma_f32_16x16x32_bf16 v[38:41], v[182:185], v[218:221], v[38:41]
	v_mfma_f32_16x16x32_bf16 v[34:37], v[202:205], v[218:221], v[34:37]
	v_mfma_f32_16x16x32_bf16 v[22:25], v[182:185], v[226:229], v[22:25]
	v_mfma_f32_16x16x32_bf16 v[18:21], v[202:205], v[226:229], v[18:21]
	v_mfma_f32_16x16x32_bf16 v[6:9], v[182:185], v[234:237], v[6:9]
	v_mfma_f32_16x16x32_bf16 v[2:5], v[202:205], v[234:237], v[2:5]
	s_setprio 0
	s_barrier
	s_add_i32 s49, 0, 0x18000
	s_add_i32 s50, 0, 0x1c000
	v_add_u32_e32 v174, s49, v152
	v_add_u32_e32 v202, s50, v152
	ds_read_b128 v[142:145], v174
	ds_read_b128 v[146:149], v174 offset:1024
	ds_read_b128 v[168:171], v174 offset:2048
	ds_read_b128 v[174:177], v174 offset:3072
	ds_read_b128 v[178:181], v202
	ds_read_b128 v[182:185], v202 offset:1024
	ds_read_b128 v[186:189], v202 offset:2048
	ds_read_b128 v[202:205], v202 offset:3072
	s_add_u32 s2, s2, 0x80000
	s_addc_u32 s3, s3, 0
	s_mov_b32 m0, s37
	v_lshl_add_u64 v[242:243], s[2:3], 0, v[136:137]
	ds_read_b128 v[206:209], v167 offset:32768
	ds_read_b128 v[210:213], v167 offset:33792
	ds_read_b128 v[214:217], v167 offset:34816
	ds_read_b128 v[218:221], v167 offset:35840
	ds_read_b128 v[222:225], v167 offset:36864
	ds_read_b128 v[226:229], v167 offset:37888
	ds_read_b128 v[230:233], v167 offset:38912
	ds_read_b128 v[234:237], v167 offset:39936
	global_load_lds_dwordx4 v[242:243], off
	v_lshl_add_u64 v[242:243], s[2:3], 0, v[132:133]
	s_mov_b32 m0, s38
	s_nop 0
	global_load_lds_dwordx4 v[242:243], off
	s_waitcnt vmcnt(8)
	s_waitcnt lgkmcnt(0)
	s_setprio 1
	s_waitcnt lgkmcnt(0)
	v_mfma_f32_16x16x32_bf16 v[126:129], v[142:145], v[206:209], v[126:129]
	v_mfma_f32_16x16x32_bf16 v[122:125], v[168:171], v[206:209], v[122:125]
	s_barrier
	v_mfma_f32_16x16x32_bf16 v[110:113], v[142:145], v[214:217], v[110:113]
	v_mfma_f32_16x16x32_bf16 v[106:109], v[168:171], v[214:217], v[106:109]
	v_mfma_f32_16x16x32_bf16 v[94:97], v[142:145], v[222:225], v[94:97]
	v_mfma_f32_16x16x32_bf16 v[90:93], v[168:171], v[222:225], v[90:93]
	v_mfma_f32_16x16x32_bf16 v[78:81], v[142:145], v[230:233], v[78:81]
	v_mfma_f32_16x16x32_bf16 v[74:77], v[168:171], v[230:233], v[74:77]
	v_mfma_f32_16x16x32_bf16 v[126:129], v[146:149], v[210:213], v[126:129]
	v_mfma_f32_16x16x32_bf16 v[122:125], v[174:177], v[210:213], v[122:125]
	v_mfma_f32_16x16x32_bf16 v[110:113], v[146:149], v[218:221], v[110:113]
	v_mfma_f32_16x16x32_bf16 v[106:109], v[174:177], v[218:221], v[106:109]
	v_mfma_f32_16x16x32_bf16 v[94:97], v[146:149], v[226:229], v[94:97]
	v_mfma_f32_16x16x32_bf16 v[90:93], v[174:177], v[226:229], v[90:93]
	v_mfma_f32_16x16x32_bf16 v[78:81], v[146:149], v[234:237], v[78:81]
	v_mfma_f32_16x16x32_bf16 v[74:77], v[174:177], v[234:237], v[74:77]
	s_setprio 0
	s_setprio 1
	v_mfma_f32_16x16x32_bf16 v[118:121], v[178:181], v[206:209], v[118:121]
	v_mfma_f32_16x16x32_bf16 v[114:117], v[186:189], v[206:209], v[114:117]
	v_mfma_f32_16x16x32_bf16 v[102:105], v[178:181], v[214:217], v[102:105]
	v_mfma_f32_16x16x32_bf16 v[98:101], v[186:189], v[214:217], v[98:101]
	v_mfma_f32_16x16x32_bf16 v[86:89], v[178:181], v[222:225], v[86:89]
	v_mfma_f32_16x16x32_bf16 v[82:85], v[186:189], v[222:225], v[82:85]
	v_mfma_f32_16x16x32_bf16 v[70:73], v[178:181], v[230:233], v[70:73]
	v_mfma_f32_16x16x32_bf16 v[66:69], v[186:189], v[230:233], v[66:69]
	v_mfma_f32_16x16x32_bf16 v[118:121], v[182:185], v[210:213], v[118:121]
	v_mfma_f32_16x16x32_bf16 v[114:117], v[202:205], v[210:213], v[114:117]
	v_mfma_f32_16x16x32_bf16 v[102:105], v[182:185], v[218:221], v[102:105]
	v_mfma_f32_16x16x32_bf16 v[98:101], v[202:205], v[218:221], v[98:101]
	v_mfma_f32_16x16x32_bf16 v[86:89], v[182:185], v[226:229], v[86:89]
	v_mfma_f32_16x16x32_bf16 v[82:85], v[202:205], v[226:229], v[82:85]
	v_mfma_f32_16x16x32_bf16 v[70:73], v[182:185], v[234:237], v[70:73]
	v_mfma_f32_16x16x32_bf16 v[66:69], v[202:205], v[234:237], v[66:69]
	s_setprio 0
	s_barrier
; #define PG8_STAGE(bufoff, gbase, voff) do { _Pragma("unroll") for (int _i = 0; _i < 2; ++_i) \
;         __builtin_amdgcn_global_load_lds((const unsigned*)((const char*)(gbase) + (voff)[_i]), (PG8_LAS unsigned*)(lds + (bufoff) + ldsw + _i * 8192), 16, 0, 0); } while (0)
; #define PG8_LDA(dst, b, h) do { _Pragma("unroll") for (int m = 0; m < 4; ++m) _Pragma("unroll") for (int k = 0; k < 2; ++k) dst[m][k] = *(const PG8_LAS bf16x8*)(lds + PG8_SA(b, h) + aoff + m * 2048 + k * 1024); } while (0)
; #define PG8_MMA(ai, bj, At, Bt) do { __builtin_amdgcn_s_setprio(1); _Pragma("unroll") for (int m = 0; m < 4; ++m) _Pragma("unroll") for (int n = 0; n < 2; ++n) _Pragma("unroll") for (int k = 0; k < 2; ++k) \
;         acc[ai][bj][m][n] = __builtin_amdgcn_mfma_f32_16x16x32_bf16(Bt[n][k], At[m][k], acc[ai][bj][m][n], 0, 0, 0); __builtin_amdgcn_s_setprio(0); } while (0)
; #define PG8_WAIT_V(n) asm volatile("s_waitcnt vmcnt(" #n ")" ::: "memory")
; #define PG8_WAIT_L(n) asm volatile("s_waitcnt lgkmcnt(" #n ")" ::: "memory")
; #define PG8_BAR __builtin_amdgcn_s_barrier()
; #define PG8_SCHED __builtin_amdgcn_sched_barrier(0)
; template <class Epi, class Sched, bool ALIGN_EPI = false, bool SP2 = false>
; __device__ __forceinline__ void gemm_phase(PG8_LAS unsigned char* lds, const Gemm g, const Sched& S, const Epi& E, const int wid_in) {
;     ...
;             PG8_LDA(At, 1, 1); PG8_STAGE(PG8_SB(1, 0), b3, voffB); PG8_STAGE(PG8_SB(1, 1), b3 + hstep, voffB); PG8_STAGE(PG8_SA(1, 0), a3, voffA);
;             PG8_WAIT_V(8); PG8_WAIT_L(0); PG8_BAR; PG8_MMA(1, 0, At, B0); PG8_MMA(1, 1, At, B1); PG8_BAR; PG8_SCHED;
	s_add_i32 s2, s49, s29
	v_lshl_add_u64 v[150:151], v[150:151], 0, s[98:99]
	s_mov_b32 m0, s2
	ds_read_b128 v[206:209], v167 offset:49152
	ds_read_b128 v[210:213], v167 offset:50176
	ds_read_b128 v[214:217], v167 offset:51200
	ds_read_b128 v[218:221], v167 offset:52224
	ds_read_b128 v[222:225], v167 offset:53248
	ds_read_b128 v[226:229], v167 offset:54272
	ds_read_b128 v[230:233], v167 offset:55296
	ds_read_b128 v[234:237], v167 offset:56320
	global_load_lds_dwordx4 v[150:151], off
	s_add_i32 m0, s2, 0x2000
	s_add_u32 s0, s0, 0x80080
	v_lshl_add_u64 v[150:151], v[190:191], 0, s[98:99]
	s_addc_u32 s1, s1, 0
	s_add_i32 s2, s50, s29
	global_load_lds_dwordx4 v[150:151], off
	v_lshl_add_u64 v[150:151], s[0:1], 0, v[134:135]
	s_mov_b32 m0, s2
	s_nop 0
	global_load_lds_dwordx4 v[150:151], off
	v_lshl_add_u64 v[150:151], s[0:1], 0, v[130:131]
	s_add_i32 m0, s2, 0x2000
	s_nop 0
	global_load_lds_dwordx4 v[150:151], off
	v_lshl_add_u64 v[150:151], v[238:239], 0, s[98:99]
	s_mov_b32 m0, s39
	s_nop 0
	global_load_lds_dwordx4 v[150:151], off
	v_lshl_add_u64 v[150:151], v[240:241], 0, s[98:99]
	s_mov_b32 m0, s40
	s_nop 0
	global_load_lds_dwordx4 v[150:151], off
	s_waitcnt vmcnt(8)
	s_waitcnt lgkmcnt(0)
	s_setprio 1
	s_waitcnt lgkmcnt(0)
	v_mfma_f32_16x16x32_bf16 v[62:65], v[142:145], v[206:209], v[62:65]
	v_mfma_f32_16x16x32_bf16 v[58:61], v[168:171], v[206:209], v[58:61]
	s_barrier
	v_mfma_f32_16x16x32_bf16 v[46:49], v[142:145], v[214:217], v[46:49]
	v_mfma_f32_16x16x32_bf16 v[42:45], v[168:171], v[214:217], v[42:45]
	v_mfma_f32_16x16x32_bf16 v[30:33], v[142:145], v[222:225], v[30:33]
	v_mfma_f32_16x16x32_bf16 v[26:29], v[168:171], v[222:225], v[26:29]
	v_mfma_f32_16x16x32_bf16 v[14:17], v[142:145], v[230:233], v[14:17]
	v_mfma_f32_16x16x32_bf16 v[10:13], v[168:171], v[230:233], v[10:13]
	v_mfma_f32_16x16x32_bf16 v[62:65], v[146:149], v[210:213], v[62:65]
	v_mfma_f32_16x16x32_bf16 v[58:61], v[174:177], v[210:213], v[58:61]
	v_mfma_f32_16x16x32_bf16 v[46:49], v[146:149], v[218:221], v[46:49]
	v_mfma_f32_16x16x32_bf16 v[42:45], v[174:177], v[218:221], v[42:45]
	v_mfma_f32_16x16x32_bf16 v[30:33], v[146:149], v[226:229], v[30:33]
	v_mfma_f32_16x16x32_bf16 v[26:29], v[174:177], v[226:229], v[26:29]
	v_mfma_f32_16x16x32_bf16 v[14:17], v[146:149], v[234:237], v[14:17]
	v_mfma_f32_16x16x32_bf16 v[10:13], v[174:177], v[234:237], v[10:13]
	s_setprio 0
	s_setprio 1
	v_mfma_f32_16x16x32_bf16 v[54:57], v[178:181], v[206:209], v[54:57]
	v_mfma_f32_16x16x32_bf16 v[50:53], v[186:189], v[206:209], v[50:53]
	v_mfma_f32_16x16x32_bf16 v[38:41], v[178:181], v[214:217], v[38:41]
	v_mfma_f32_16x16x32_bf16 v[34:37], v[186:189], v[214:217], v[34:37]
	v_mfma_f32_16x16x32_bf16 v[22:25], v[178:181], v[222:225], v[22:25]
	v_mfma_f32_16x16x32_bf16 v[18:21], v[186:189], v[222:225], v[18:21]
	v_mfma_f32_16x16x32_bf16 v[6:9], v[178:181], v[230:233], v[6:9]
	v_mfma_f32_16x16x32_bf16 v[2:5], v[186:189], v[230:233], v[2:5]
	v_mfma_f32_16x16x32_bf16 v[54:57], v[182:185], v[210:213], v[54:57]
	v_mfma_f32_16x16x32_bf16 v[50:53], v[202:205], v[210:213], v[50:53]
	v_mfma_f32_16x16x32_bf16 v[38:41], v[182:185], v[218:221], v[38:41]
	v_mfma_f32_16x16x32_bf16 v[34:37], v[202:205], v[218:221], v[34:37]
	v_mfma_f32_16x16x32_bf16 v[22:25], v[182:185], v[226:229], v[22:25]
	v_mfma_f32_16x16x32_bf16 v[18:21], v[202:205], v[226:229], v[18:21]
	v_mfma_f32_16x16x32_bf16 v[6:9], v[182:185], v[234:237], v[6:9]
	v_mfma_f32_16x16x32_bf16 v[2:5], v[202:205], v[234:237], v[2:5]
	s_setprio 0
	s_barrier
	s_add_i32 s48, s48, 2
	s_add_u32 s24, s24, 0x100
	s_addc_u32 s25, s25, 0
	s_add_u32 s46, s46, 0x100
	s_addc_u32 s47, s47, 0
	s_cmp_gt_u32 s48, 29
	s_cbranch_scc0 .LBB0_484
	s_and_b64 vcc, exec, s[14:15]
	s_cbranch_vccz .LBB0_487
	s_barrier

; #define PG8_STAGE(bufoff, gbase, voff) do { _Pragma("unroll") for (int _i = 0; _i < 2; ++_i) \
;         __builtin_amdgcn_global_load_lds((const unsigned*)((const char*)(gbase) + (voff)[_i]), (PG8_LAS unsigned*)(lds + (bufoff) + ldsw + _i * 8192), 16, 0, 0); } while (0)
; #define PG8_LDA(dst, b, h) do { _Pragma("unroll") for (int m = 0; m < 4; ++m) _Pragma("unroll") for (int k = 0; k < 2; ++k) dst[m][k] = *(const PG8_LAS bf16x8*)(lds + PG8_SA(b, h) + aoff + m * 2048 + k * 1024); } while (0)
; #define PG8_LDB(dst, b, h) do { _Pragma("unroll") for (int n = 0; n < 2; ++n) _Pragma("unroll") for (int k = 0; k < 2; ++k) dst[n][k] = *(const PG8_LAS bf16x8*)(lds + PG8_SB(b, h) + boff + n * 2048 + k * 1024); } while (0)
; #define PG8_MMA(ai, bj, At, Bt) do { __builtin_amdgcn_s_setprio(1); _Pragma("unroll") for (int m = 0; m < 4; ++m) _Pragma("unroll") for (int n = 0; n < 2; ++n) _Pragma("unroll") for (int k = 0; k < 2; ++k) \
;         acc[ai][bj][m][n] = __builtin_amdgcn_mfma_f32_16x16x32_bf16(Bt[n][k], At[m][k], acc[ai][bj][m][n], 0, 0, 0); __builtin_amdgcn_s_setprio(0); } while (0)
; #define PG8_WAIT_V(n) asm volatile("s_waitcnt vmcnt(" #n ")" ::: "memory")
; #define PG8_WAIT_L(n) asm volatile("s_waitcnt lgkmcnt(" #n ")" ::: "memory")
; #define PG8_BAR __builtin_amdgcn_s_barrier()
; #define PG8_SCHED __builtin_amdgcn_sched_barrier(0)
; template <class Epi, class Sched, bool ALIGN_EPI = false, bool SP2 = false>
; __device__ __forceinline__ void gemm_phase(PG8_LAS unsigned char* lds, const Gemm g, const Sched& S, const Epi& E, const int wid_in) {
;     ...
;             PG8_LDB(B0, 0, 0); PG8_LDB(B1, 0, 1); PG8_SCHED; PG8_LDA(At, 0, 0); PG8_STAGE(PG8_SA(1, 1), a1 + hstepA, voffA);
;             PG8_WAIT_V(8); PG8_WAIT_L(0); PG8_BAR; PG8_MMA(0, 0, At, B0); PG8_MMA(0, 1, At, B1); PG8_BAR; PG8_SCHED;
;             PG8_LDA(At, 0, 1); PG8_STAGE(PG8_SB(0, 0), b2, voffB); PG8_STAGE(PG8_SB(0, 1), b2 + hstep, voffB); PG8_STAGE(PG8_SA(0, 0), a2, voffA);
;             PG8_WAIT_V(8); PG8_WAIT_L(0); PG8_BAR; PG8_MMA(1, 0, At, B0); PG8_MMA(1, 1, At, B1); PG8_BAR; PG8_SCHED;
.LBB0_545:
	s_add_u32 s2, s0, 0xffe00080
	s_addc_u32 s3, s1, -1
	s_add_i32 s49, 0, 0x10000
	s_cmpk_eq_i32 s48, 0x7c
	s_cselect_b32 s9, s21, s3
	s_cselect_b32 s8, s46, s2
	v_add_u32_e32 v145, s49, v147
	s_cselect_b32 s3, s19, s27
	s_cselect_b32 s2, s47, s26
	s_add_i32 s52, 0, 0x14000
	ds_read_b128 v[166:169], v145
	ds_read_b128 v[174:177], v145 offset:1024
	ds_read_b128 v[178:181], v145 offset:2048
	ds_read_b128 v[182:185], v145 offset:3072
	v_add_u32_e32 v145, s52, v147
	ds_read_b128 v[186:189], v145
	ds_read_b128 v[202:205], v145 offset:1024
	ds_read_b128 v[206:209], v145 offset:2048
	ds_read_b128 v[210:213], v145 offset:3072
	v_lshl_add_u64 v[152:153], s[0:1], 0, v[140:141]
	s_add_i32 m0, s36, 0xc000
	ds_read_b128 v[214:217], v150
	ds_read_b128 v[218:221], v150 offset:1024
	ds_read_b128 v[222:225], v150 offset:2048
	ds_read_b128 v[226:229], v150 offset:3072
	ds_read_b128 v[230:233], v150 offset:4096
	ds_read_b128 v[234:237], v150 offset:5120
	ds_read_b128 v[238:241], v150 offset:6144
	ds_read_b128 v[242:245], v150 offset:7168
	global_load_lds_dwordx4 v[152:153], off
	v_lshl_add_u64 v[152:153], s[0:1], 0, v[142:143]
	s_add_i32 m0, s36, 0xe000
	s_nop 0
	global_load_lds_dwordx4 v[152:153], off
	s_waitcnt vmcnt(8)
	s_waitcnt lgkmcnt(0)
	s_setprio 1
	s_waitcnt lgkmcnt(0)
	v_mfma_f32_16x16x32_bf16 v[118:121], v[166:169], v[214:217], v[118:121]
	v_mfma_f32_16x16x32_bf16 v[114:117], v[178:181], v[214:217], v[114:117]
	s_barrier
	v_mfma_f32_16x16x32_bf16 v[98:101], v[166:169], v[222:225], v[98:101]
	v_mfma_f32_16x16x32_bf16 v[106:109], v[178:181], v[222:225], v[106:109]
	v_mfma_f32_16x16x32_bf16 v[82:85], v[166:169], v[230:233], v[82:85]
	v_mfma_f32_16x16x32_bf16 v[90:93], v[178:181], v[230:233], v[90:93]
	v_mfma_f32_16x16x32_bf16 v[74:77], v[166:169], v[238:241], v[74:77]
	v_mfma_f32_16x16x32_bf16 v[66:69], v[178:181], v[238:241], v[66:69]
	v_mfma_f32_16x16x32_bf16 v[118:121], v[174:177], v[218:221], v[118:121]
	v_mfma_f32_16x16x32_bf16 v[114:117], v[182:185], v[218:221], v[114:117]
	v_mfma_f32_16x16x32_bf16 v[98:101], v[174:177], v[226:229], v[98:101]
	v_mfma_f32_16x16x32_bf16 v[106:109], v[182:185], v[226:229], v[106:109]
	v_mfma_f32_16x16x32_bf16 v[82:85], v[174:177], v[234:237], v[82:85]
	v_mfma_f32_16x16x32_bf16 v[90:93], v[182:185], v[234:237], v[90:93]
	v_mfma_f32_16x16x32_bf16 v[74:77], v[174:177], v[242:245], v[74:77]
	v_mfma_f32_16x16x32_bf16 v[66:69], v[182:185], v[242:245], v[66:69]
	s_setprio 0
	s_setprio 1
	v_mfma_f32_16x16x32_bf16 v[122:125], v[186:189], v[214:217], v[122:125]
	v_mfma_f32_16x16x32_bf16 v[126:129], v[206:209], v[214:217], v[126:129]
	v_mfma_f32_16x16x32_bf16 v[102:105], v[186:189], v[222:225], v[102:105]
	v_mfma_f32_16x16x32_bf16 v[110:113], v[206:209], v[222:225], v[110:113]
	v_mfma_f32_16x16x32_bf16 v[86:89], v[186:189], v[230:233], v[86:89]
	v_mfma_f32_16x16x32_bf16 v[94:97], v[206:209], v[230:233], v[94:97]
	v_mfma_f32_16x16x32_bf16 v[70:73], v[186:189], v[238:241], v[70:73]
	v_mfma_f32_16x16x32_bf16 v[78:81], v[206:209], v[238:241], v[78:81]
	v_mfma_f32_16x16x32_bf16 v[122:125], v[202:205], v[218:221], v[122:125]
	v_mfma_f32_16x16x32_bf16 v[126:129], v[210:213], v[218:221], v[126:129]
	v_mfma_f32_16x16x32_bf16 v[102:105], v[202:205], v[226:229], v[102:105]
	v_mfma_f32_16x16x32_bf16 v[110:113], v[210:213], v[226:229], v[110:113]
	v_mfma_f32_16x16x32_bf16 v[86:89], v[202:205], v[234:237], v[86:89]
	v_mfma_f32_16x16x32_bf16 v[94:97], v[210:213], v[234:237], v[94:97]
	v_mfma_f32_16x16x32_bf16 v[70:73], v[202:205], v[242:245], v[70:73]
	v_mfma_f32_16x16x32_bf16 v[78:81], v[210:213], v[242:245], v[78:81]
	s_setprio 0
	s_barrier
	s_add_i32 s49, s49, s35
	v_lshl_add_u64 v[152:153], s[2:3], 0, v[134:135]
	s_mov_b32 m0, s49
	ds_read_b128 v[214:217], v150 offset:16384
	ds_read_b128 v[218:221], v150 offset:17408
	ds_read_b128 v[222:225], v150 offset:18432
	ds_read_b128 v[226:229], v150 offset:19456
	ds_read_b128 v[230:233], v150 offset:20480
	ds_read_b128 v[234:237], v150 offset:21504
	ds_read_b128 v[238:241], v150 offset:22528
	ds_read_b128 v[242:245], v150 offset:23552
	global_load_lds_dwordx4 v[152:153], off
	s_add_i32 m0, s49, 0x2000
	s_add_u32 s50, s2, 0x200000
	v_lshl_add_u64 v[170:171], s[2:3], 0, v[130:131]
	s_addc_u32 s51, s3, 0
	s_add_i32 s49, s52, s35
	global_load_lds_dwordx4 v[170:171], off
	v_lshl_add_u64 v[190:191], s[50:51], 0, v[134:135]
	s_mov_b32 m0, s49
	v_lshl_add_u64 v[246:247], s[8:9], 0, v[132:133]
	global_load_lds_dwordx4 v[190:191], off
	v_lshl_add_u64 v[190:191], s[50:51], 0, v[130:131]
	s_add_i32 m0, s49, 0x2000
	s_nop 0
	global_load_lds_dwordx4 v[190:191], off
	v_lshl_add_u64 v[190:191], s[8:9], 0, v[136:137]
	s_mov_b32 m0, s36
	s_nop 0
	global_load_lds_dwordx4 v[190:191], off
	s_mov_b32 m0, s37
	s_nop 0
	global_load_lds_dwordx4 v[246:247], off
	s_waitcnt vmcnt(8)
	s_waitcnt lgkmcnt(0)
	s_setprio 1
	s_waitcnt lgkmcnt(0)
	v_mfma_f32_16x16x32_bf16 v[34:37], v[166:169], v[214:217], v[34:37]
	v_mfma_f32_16x16x32_bf16 v[46:49], v[178:181], v[214:217], v[46:49]
	s_barrier
; #define PG8_STAGE(bufoff, gbase, voff) do { _Pragma("unroll") for (int _i = 0; _i < 2; ++_i) \
;         __builtin_amdgcn_global_load_lds((const unsigned*)((const char*)(gbase) + (voff)[_i]), (PG8_LAS unsigned*)(lds + (bufoff) + ldsw + _i * 8192), 16, 0, 0); } while (0)
; #define PG8_LDA(dst, b, h) do { _Pragma("unroll") for (int m = 0; m < 4; ++m) _Pragma("unroll") for (int k = 0; k < 2; ++k) dst[m][k] = *(const PG8_LAS bf16x8*)(lds + PG8_SA(b, h) + aoff + m * 2048 + k * 1024); } while (0)
; #define PG8_LDB(dst, b, h) do { _Pragma("unroll") for (int n = 0; n < 2; ++n) _Pragma("unroll") for (int k = 0; k < 2; ++k) dst[n][k] = *(const PG8_LAS bf16x8*)(lds + PG8_SB(b, h) + boff + n * 2048 + k * 1024); } while (0)
; #define PG8_MMA(ai, bj, At, Bt) do { __builtin_amdgcn_s_setprio(1); _Pragma("unroll") for (int m = 0; m < 4; ++m) _Pragma("unroll") for (int n = 0; n < 2; ++n) _Pragma("unroll") for (int k = 0; k < 2; ++k) \
;         acc[ai][bj][m][n] = __builtin_amdgcn_mfma_f32_16x16x32_bf16(Bt[n][k], At[m][k], acc[ai][bj][m][n], 0, 0, 0); __builtin_amdgcn_s_setprio(0); } while (0)
; #define PG8_WAIT_V(n) asm volatile("s_waitcnt vmcnt(" #n ")" ::: "memory")
; #define PG8_WAIT_L(n) asm volatile("s_waitcnt lgkmcnt(" #n ")" ::: "memory")
; #define PG8_BAR __builtin_amdgcn_s_barrier()
; #define PG8_SCHED __builtin_amdgcn_sched_barrier(0)
; template <class Epi, class Sched, bool ALIGN_EPI = false, bool SP2 = false>
; __device__ __forceinline__ void gemm_phase(PG8_LAS unsigned char* lds, const Gemm g, const Sched& S, const Epi& E, const int wid_in) {
;     ...
;             PG8_WAIT_V(8); PG8_WAIT_L(0); PG8_BAR; PG8_MMA(1, 0, At, B0); PG8_MMA(1, 1, At, B1); PG8_BAR; PG8_SCHED;
;             PG8_LDB(B0, 1, 0); PG8_LDB(B1, 1, 1); PG8_SCHED; PG8_LDA(At, 1, 0); PG8_STAGE(PG8_SA(0, 1), a2 + hstepA, voffA);
;             PG8_WAIT_V(8); PG8_WAIT_L(0); PG8_BAR; PG8_MMA(0, 0, At, B0); PG8_MMA(0, 1, At, B1); PG8_BAR; PG8_SCHED;
;             PG8_LDA(At, 1, 1); PG8_STAGE(PG8_SB(1, 0), b3, voffB); PG8_STAGE(PG8_SB(1, 1), b3 + hstep, voffB); PG8_STAGE(PG8_SA(1, 0), a3, voffA);
	v_mfma_f32_16x16x32_bf16 v[10:13], v[166:169], v[222:225], v[10:13]
	v_mfma_f32_16x16x32_bf16 v[6:9], v[178:181], v[222:225], v[6:9]
	v_mfma_f32_16x16x32_bf16 v[42:45], v[166:169], v[230:233], v[42:45]
	v_mfma_f32_16x16x32_bf16 v[58:61], v[178:181], v[230:233], v[58:61]
	v_mfma_f32_16x16x32_bf16 v[22:25], v[166:169], v[238:241], v[22:25]
	v_mfma_f32_16x16x32_bf16 v[2:5], v[178:181], v[238:241], v[2:5]
	v_mfma_f32_16x16x32_bf16 v[34:37], v[174:177], v[218:221], v[34:37]
	v_mfma_f32_16x16x32_bf16 v[46:49], v[182:185], v[218:221], v[46:49]
	v_mfma_f32_16x16x32_bf16 v[10:13], v[174:177], v[226:229], v[10:13]
	v_mfma_f32_16x16x32_bf16 v[6:9], v[182:185], v[226:229], v[6:9]
	v_mfma_f32_16x16x32_bf16 v[42:45], v[174:177], v[234:237], v[42:45]
	v_mfma_f32_16x16x32_bf16 v[58:61], v[182:185], v[234:237], v[58:61]
	v_mfma_f32_16x16x32_bf16 v[22:25], v[174:177], v[242:245], v[22:25]
	v_mfma_f32_16x16x32_bf16 v[2:5], v[182:185], v[242:245], v[2:5]
	s_setprio 0
	s_setprio 1
	v_mfma_f32_16x16x32_bf16 v[38:41], v[186:189], v[214:217], v[38:41]
	v_mfma_f32_16x16x32_bf16 v[54:57], v[206:209], v[214:217], v[54:57]
	v_mfma_f32_16x16x32_bf16 v[14:17], v[186:189], v[222:225], v[14:17]
	v_mfma_f32_16x16x32_bf16 v[26:29], v[206:209], v[222:225], v[26:29]
	v_mfma_f32_16x16x32_bf16 v[50:53], v[186:189], v[230:233], v[50:53]
	v_mfma_f32_16x16x32_bf16 v[62:65], v[206:209], v[230:233], v[62:65]
	v_mfma_f32_16x16x32_bf16 v[18:21], v[186:189], v[238:241], v[18:21]
	v_mfma_f32_16x16x32_bf16 v[30:33], v[206:209], v[238:241], v[30:33]
	v_mfma_f32_16x16x32_bf16 v[38:41], v[202:205], v[218:221], v[38:41]
	v_mfma_f32_16x16x32_bf16 v[54:57], v[210:213], v[218:221], v[54:57]
	v_mfma_f32_16x16x32_bf16 v[14:17], v[202:205], v[226:229], v[14:17]
	v_mfma_f32_16x16x32_bf16 v[26:29], v[210:213], v[226:229], v[26:29]
	v_mfma_f32_16x16x32_bf16 v[50:53], v[202:205], v[234:237], v[50:53]
	v_mfma_f32_16x16x32_bf16 v[62:65], v[210:213], v[234:237], v[62:65]
	v_mfma_f32_16x16x32_bf16 v[18:21], v[202:205], v[242:245], v[18:21]
	v_mfma_f32_16x16x32_bf16 v[30:33], v[210:213], v[242:245], v[30:33]
	s_setprio 0
	s_barrier
	s_add_i32 s49, 0, 0x18000
	v_add_u32_e32 v145, s49, v147
	s_add_i32 s50, 0, 0x1c000
	ds_read_b128 v[166:169], v145
	ds_read_b128 v[174:177], v145 offset:1024
	ds_read_b128 v[178:181], v145 offset:2048
	ds_read_b128 v[182:185], v145 offset:3072
	v_add_u32_e32 v145, s50, v147
	ds_read_b128 v[186:189], v145
	ds_read_b128 v[202:205], v145 offset:1024
	ds_read_b128 v[206:209], v145 offset:2048
	ds_read_b128 v[210:213], v145 offset:3072
	s_add_u32 s8, s8, 0x200000
	s_addc_u32 s9, s9, 0
	s_mov_b32 m0, s38
	v_lshl_add_u64 v[248:249], s[8:9], 0, v[136:137]
	ds_read_b128 v[214:217], v150 offset:32768
	ds_read_b128 v[218:221], v150 offset:33792
	ds_read_b128 v[222:225], v150 offset:34816
	ds_read_b128 v[226:229], v150 offset:35840
	ds_read_b128 v[230:233], v150 offset:36864
	ds_read_b128 v[234:237], v150 offset:37888
	ds_read_b128 v[238:241], v150 offset:38912
	ds_read_b128 v[242:245], v150 offset:39936
	global_load_lds_dwordx4 v[248:249], off
	v_lshl_add_u64 v[248:249], s[8:9], 0, v[132:133]
	s_mov_b32 m0, s39
	s_nop 0
	global_load_lds_dwordx4 v[248:249], off
	s_waitcnt vmcnt(8)
	s_waitcnt lgkmcnt(0)
	s_setprio 1
	s_waitcnt lgkmcnt(0)
	v_mfma_f32_16x16x32_bf16 v[118:121], v[166:169], v[214:217], v[118:121]
	v_mfma_f32_16x16x32_bf16 v[114:117], v[178:181], v[214:217], v[114:117]
	s_barrier
	v_mfma_f32_16x16x32_bf16 v[98:101], v[166:169], v[222:225], v[98:101]
	v_mfma_f32_16x16x32_bf16 v[106:109], v[178:181], v[222:225], v[106:109]
	v_mfma_f32_16x16x32_bf16 v[82:85], v[166:169], v[230:233], v[82:85]
	v_mfma_f32_16x16x32_bf16 v[90:93], v[178:181], v[230:233], v[90:93]
	v_mfma_f32_16x16x32_bf16 v[74:77], v[166:169], v[238:241], v[74:77]
	v_mfma_f32_16x16x32_bf16 v[66:69], v[178:181], v[238:241], v[66:69]
	v_mfma_f32_16x16x32_bf16 v[118:121], v[174:177], v[218:221], v[118:121]
	v_mfma_f32_16x16x32_bf16 v[114:117], v[182:185], v[218:221], v[114:117]
	v_mfma_f32_16x16x32_bf16 v[98:101], v[174:177], v[226:229], v[98:101]
	v_mfma_f32_16x16x32_bf16 v[106:109], v[182:185], v[226:229], v[106:109]
	v_mfma_f32_16x16x32_bf16 v[82:85], v[174:177], v[234:237], v[82:85]
	v_mfma_f32_16x16x32_bf16 v[90:93], v[182:185], v[234:237], v[90:93]
	v_mfma_f32_16x16x32_bf16 v[74:77], v[174:177], v[242:245], v[74:77]
	v_mfma_f32_16x16x32_bf16 v[66:69], v[182:185], v[242:245], v[66:69]
	s_setprio 0
	s_setprio 1
	v_mfma_f32_16x16x32_bf16 v[122:125], v[186:189], v[214:217], v[122:125]
	v_mfma_f32_16x16x32_bf16 v[126:129], v[206:209], v[214:217], v[126:129]
	v_mfma_f32_16x16x32_bf16 v[102:105], v[186:189], v[222:225], v[102:105]
	v_mfma_f32_16x16x32_bf16 v[110:113], v[206:209], v[222:225], v[110:113]
	v_mfma_f32_16x16x32_bf16 v[86:89], v[186:189], v[230:233], v[86:89]
	v_mfma_f32_16x16x32_bf16 v[94:97], v[206:209], v[230:233], v[94:97]
	v_mfma_f32_16x16x32_bf16 v[70:73], v[186:189], v[238:241], v[70:73]
	v_mfma_f32_16x16x32_bf16 v[78:81], v[206:209], v[238:241], v[78:81]
	v_mfma_f32_16x16x32_bf16 v[122:125], v[202:205], v[218:221], v[122:125]
	v_mfma_f32_16x16x32_bf16 v[126:129], v[210:213], v[218:221], v[126:129]
	v_mfma_f32_16x16x32_bf16 v[102:105], v[202:205], v[226:229], v[102:105]
	v_mfma_f32_16x16x32_bf16 v[110:113], v[210:213], v[226:229], v[110:113]
	v_mfma_f32_16x16x32_bf16 v[86:89], v[202:205], v[234:237], v[86:89]
	v_mfma_f32_16x16x32_bf16 v[94:97], v[210:213], v[234:237], v[94:97]
	v_mfma_f32_16x16x32_bf16 v[70:73], v[202:205], v[242:245], v[70:73]
	v_mfma_f32_16x16x32_bf16 v[78:81], v[210:213], v[242:245], v[78:81]
	s_setprio 0
	s_barrier
; #define PG8_STAGE(bufoff, gbase, voff) do { _Pragma("unroll") for (int _i = 0; _i < 2; ++_i) \
;         __builtin_amdgcn_global_load_lds((const unsigned*)((const char*)(gbase) + (voff)[_i]), (PG8_LAS unsigned*)(lds + (bufoff) + ldsw + _i * 8192), 16, 0, 0); } while (0)
; #define PG8_LDA(dst, b, h) do { _Pragma("unroll") for (int m = 0; m < 4; ++m) _Pragma("unroll") for (int k = 0; k < 2; ++k) dst[m][k] = *(const PG8_LAS bf16x8*)(lds + PG8_SA(b, h) + aoff + m * 2048 + k * 1024); } while (0)
; #define PG8_MMA(ai, bj, At, Bt) do { __builtin_amdgcn_s_setprio(1); _Pragma("unroll") for (int m = 0; m < 4; ++m) _Pragma("unroll") for (int n = 0; n < 2; ++n) _Pragma("unroll") for (int k = 0; k < 2; ++k) \
;         acc[ai][bj][m][n] = __builtin_amdgcn_mfma_f32_16x16x32_bf16(Bt[n][k], At[m][k], acc[ai][bj][m][n], 0, 0, 0); __builtin_amdgcn_s_setprio(0); } while (0)
; #define PG8_WAIT_V(n) asm volatile("s_waitcnt vmcnt(" #n ")" ::: "memory")
; #define PG8_WAIT_L(n) asm volatile("s_waitcnt lgkmcnt(" #n ")" ::: "memory")
; #define PG8_BAR __builtin_amdgcn_s_barrier()
; #define PG8_SCHED __builtin_amdgcn_sched_barrier(0)
; template <class Epi, class Sched, bool ALIGN_EPI = false, bool SP2 = false>
; __device__ __forceinline__ void gemm_phase(PG8_LAS unsigned char* lds, const Gemm g, const Sched& S, const Epi& E, const int wid_in) {
;     ...
;             PG8_LDA(At, 1, 1); PG8_STAGE(PG8_SB(1, 0), b3, voffB); PG8_STAGE(PG8_SB(1, 1), b3 + hstep, voffB); PG8_STAGE(PG8_SA(1, 0), a3, voffA);
;             PG8_WAIT_V(8); PG8_WAIT_L(0); PG8_BAR; PG8_MMA(1, 0, At, B0); PG8_MMA(1, 1, At, B1); PG8_BAR; PG8_SCHED;
	s_add_i32 s8, s49, s35
	v_lshl_add_u64 v[152:153], v[152:153], 0, s[98:99]
	s_mov_b32 m0, s8
	ds_read_b128 v[214:217], v150 offset:49152
	ds_read_b128 v[218:221], v150 offset:50176
	ds_read_b128 v[222:225], v150 offset:51200
	ds_read_b128 v[226:229], v150 offset:52224
	ds_read_b128 v[230:233], v150 offset:53248
	ds_read_b128 v[234:237], v150 offset:54272
	ds_read_b128 v[238:241], v150 offset:55296
	ds_read_b128 v[242:245], v150 offset:56320
	global_load_lds_dwordx4 v[152:153], off
	s_add_i32 m0, s8, 0x2000
	s_add_u32 s2, s2, 0x200080
	v_lshl_add_u64 v[152:153], v[170:171], 0, s[98:99]
	s_addc_u32 s3, s3, 0
	s_add_i32 s8, s50, s35
	global_load_lds_dwordx4 v[152:153], off
	v_lshl_add_u64 v[152:153], s[2:3], 0, v[134:135]
	s_mov_b32 m0, s8
	s_nop 0
	global_load_lds_dwordx4 v[152:153], off
	v_lshl_add_u64 v[152:153], s[2:3], 0, v[130:131]
	s_add_i32 m0, s8, 0x2000
	s_nop 0
	global_load_lds_dwordx4 v[152:153], off
	v_lshl_add_u64 v[152:153], v[190:191], 0, s[98:99]
	s_mov_b32 m0, s42
	s_nop 0
	global_load_lds_dwordx4 v[152:153], off
	v_lshl_add_u64 v[152:153], v[246:247], 0, s[98:99]
	s_mov_b32 m0, s43
	s_nop 0
	global_load_lds_dwordx4 v[152:153], off
	s_waitcnt vmcnt(8)
	s_waitcnt lgkmcnt(0)
	s_setprio 1
	s_waitcnt lgkmcnt(0)
	v_mfma_f32_16x16x32_bf16 v[34:37], v[166:169], v[214:217], v[34:37]
	v_mfma_f32_16x16x32_bf16 v[46:49], v[178:181], v[214:217], v[46:49]
	s_barrier
	v_mfma_f32_16x16x32_bf16 v[10:13], v[166:169], v[222:225], v[10:13]
	v_mfma_f32_16x16x32_bf16 v[6:9], v[178:181], v[222:225], v[6:9]
	v_mfma_f32_16x16x32_bf16 v[42:45], v[166:169], v[230:233], v[42:45]
	v_mfma_f32_16x16x32_bf16 v[58:61], v[178:181], v[230:233], v[58:61]
	v_mfma_f32_16x16x32_bf16 v[22:25], v[166:169], v[238:241], v[22:25]
	v_mfma_f32_16x16x32_bf16 v[2:5], v[178:181], v[238:241], v[2:5]
	v_mfma_f32_16x16x32_bf16 v[34:37], v[174:177], v[218:221], v[34:37]
	v_mfma_f32_16x16x32_bf16 v[46:49], v[182:185], v[218:221], v[46:49]
	v_mfma_f32_16x16x32_bf16 v[10:13], v[174:177], v[226:229], v[10:13]
	v_mfma_f32_16x16x32_bf16 v[6:9], v[182:185], v[226:229], v[6:9]
	v_mfma_f32_16x16x32_bf16 v[42:45], v[174:177], v[234:237], v[42:45]
	v_mfma_f32_16x16x32_bf16 v[58:61], v[182:185], v[234:237], v[58:61]
	v_mfma_f32_16x16x32_bf16 v[22:25], v[174:177], v[242:245], v[22:25]
	v_mfma_f32_16x16x32_bf16 v[2:5], v[182:185], v[242:245], v[2:5]
	s_setprio 0
	s_setprio 1
	v_mfma_f32_16x16x32_bf16 v[38:41], v[186:189], v[214:217], v[38:41]
	v_mfma_f32_16x16x32_bf16 v[54:57], v[206:209], v[214:217], v[54:57]
	v_mfma_f32_16x16x32_bf16 v[14:17], v[186:189], v[222:225], v[14:17]
	v_mfma_f32_16x16x32_bf16 v[26:29], v[206:209], v[222:225], v[26:29]
	v_mfma_f32_16x16x32_bf16 v[50:53], v[186:189], v[230:233], v[50:53]
	v_mfma_f32_16x16x32_bf16 v[62:65], v[206:209], v[230:233], v[62:65]
	v_mfma_f32_16x16x32_bf16 v[18:21], v[186:189], v[238:241], v[18:21]
	v_mfma_f32_16x16x32_bf16 v[30:33], v[206:209], v[238:241], v[30:33]
	v_mfma_f32_16x16x32_bf16 v[38:41], v[202:205], v[218:221], v[38:41]
	v_mfma_f32_16x16x32_bf16 v[54:57], v[210:213], v[218:221], v[54:57]
	v_mfma_f32_16x16x32_bf16 v[14:17], v[202:205], v[226:229], v[14:17]
	v_mfma_f32_16x16x32_bf16 v[26:29], v[210:213], v[226:229], v[26:29]
	v_mfma_f32_16x16x32_bf16 v[50:53], v[202:205], v[234:237], v[50:53]
	v_mfma_f32_16x16x32_bf16 v[62:65], v[210:213], v[234:237], v[62:65]
	v_mfma_f32_16x16x32_bf16 v[18:21], v[202:205], v[242:245], v[18:21]
	v_mfma_f32_16x16x32_bf16 v[30:33], v[210:213], v[242:245], v[30:33]
	s_setprio 0
	s_barrier
	s_add_i32 s48, s48, 2
	s_add_u32 s0, s0, 0x100
	s_addc_u32 s1, s1, 0
	s_add_u32 s26, s26, 0x100
	s_addc_u32 s27, s27, 0
	s_cmpk_gt_u32 s48, 0x7d
	s_cbranch_scc0 .LBB0_545
	s_and_b64 vcc, exec, s[14:15]
	s_cbranch_vccz .LBB0_548
	s_barrier
